# speedup vs baseline: 1.0061x; 1.0061x over previous
; #define WAIT_V(n) asm volatile("s_waitcnt vmcnt(" #n ")" ::: "memory")
; #define WAIT_L(n) asm volatile("s_waitcnt lgkmcnt(" #n ")" ::: "memory")
; #define BAR __builtin_amdgcn_s_barrier()
; #define SCHED __builtin_amdgcn_sched_barrier(0)
; template <int MODE>
; __device__ __forceinline__ void gemm_tile(const int ph, const int which, const int pm, const int pn) {
;     ...
;   for (int t = 0; t < nt - 2; t += 2) {
;     LDB(B0, 0, 0); SCHED; LDA(At, 0, 0); STAGE(SA(1, 1), RA, brow + HALF, t + 1);
;     WAIT_L(8); BAR; WAIT_L(0); MMA(0, 0, At, B0); BAR; SCHED;
;     LDB(B1, 0, 1); STAGE(SB(0, 0), RB, bcol, t + 2);
;     BAR; WAIT_L(0); MMA(0, 1, At, B1); BAR;
;     LDA(At, 0, 1); STAGE(SA(0, 0), RA, brow, t + 2);
;     BAR; WAIT_L(0); MMA(1, 0, At, B0); BAR; SCHED;
;     STAGE(SB(0, 1), RB, bcolB, t + 2);
;     WAIT_V(6); BAR; MMA(1, 1, At, B1); BAR;
.LBB0_131:
	ds_read_b128 v[160:163], v158
	ds_read_b128 v[164:167], v158 offset:1024
	ds_read_b128 v[168:171], v158 offset:2048
	ds_read_b128 v[172:175], v158 offset:3072
	s_add_i32 s12, s16, s25
	v_readfirstlane_b32 s28, v155
	s_add_i32 s13, s12, 0x80
	s_mov_b32 m0, s28
	ds_read_b128 v[176:179], v137
	ds_read_b128 v[180:183], v137 offset:1024
	ds_read_b128 v[184:187], v136
	ds_read_b128 v[188:191], v136 offset:1024
	ds_read_b128 v[192:195], v135
	ds_read_b128 v[196:199], v135 offset:1024
	ds_read_b128 v[200:203], v134
	ds_read_b128 v[204:207], v134 offset:1024
	buffer_load_dwordx4 v138, s[4:7], s13 offen lds
	s_add_i32 s13, s3, s25
	v_readfirstlane_b32 s29, v153
	s_add_i32 s28, s13, 0x80
	s_mov_b32 m0, s29
	s_nop 0
	buffer_load_dwordx4 v138, s[4:7], s28 offen lds
	s_waitcnt lgkmcnt(8)
	s_barrier
	s_waitcnt lgkmcnt(0)
	s_setprio 1
	s_waitcnt lgkmcnt(7)
	v_mfma_f32_16x16x32_bf16 v[126:129], v[160:163], v[176:179], v[126:129]
	v_mfma_f32_16x16x32_bf16 v[122:125], v[168:171], v[176:179], v[122:125]
	s_waitcnt lgkmcnt(5)
	v_mfma_f32_16x16x32_bf16 v[118:121], v[160:163], v[184:187], v[118:121]
	v_mfma_f32_16x16x32_bf16 v[114:117], v[168:171], v[184:187], v[114:117]
	s_waitcnt lgkmcnt(3)
	v_mfma_f32_16x16x32_bf16 v[110:113], v[160:163], v[192:195], v[110:113]
	v_mfma_f32_16x16x32_bf16 v[106:109], v[168:171], v[192:195], v[106:109]
	s_waitcnt lgkmcnt(1)
	v_mfma_f32_16x16x32_bf16 v[102:105], v[160:163], v[200:203], v[102:105]
	v_mfma_f32_16x16x32_bf16 v[98:101], v[168:171], v[200:203], v[98:101]
	v_mfma_f32_16x16x32_bf16 v[126:129], v[164:167], v[180:183], v[126:129]
	v_mfma_f32_16x16x32_bf16 v[122:125], v[172:175], v[180:183], v[122:125]
	v_mfma_f32_16x16x32_bf16 v[118:121], v[164:167], v[188:191], v[118:121]
	v_mfma_f32_16x16x32_bf16 v[114:117], v[172:175], v[188:191], v[114:117]
	v_mfma_f32_16x16x32_bf16 v[110:113], v[164:167], v[196:199], v[110:113]
	v_mfma_f32_16x16x32_bf16 v[106:109], v[172:175], v[196:199], v[106:109]
	s_waitcnt lgkmcnt(0)
	v_mfma_f32_16x16x32_bf16 v[102:105], v[164:167], v[204:207], v[102:105]
	v_mfma_f32_16x16x32_bf16 v[98:101], v[172:175], v[204:207], v[98:101]
	s_setprio 0
	s_barrier
	s_add_i32 s28, s24, s25
	v_readfirstlane_b32 s38, v141
	s_add_i32 s29, s28, 0x100
	s_mov_b32 m0, s38
	ds_read_b128 v[236:239], v157
	ds_read_b128 v[240:243], v157 offset:1024
	ds_read_b128 v[244:247], v157 offset:2048
	ds_read_b128 v[248:251], v157 offset:3072
	buffer_load_dwordx4 v138, s[68:71], s29 offen lds
	s_add_i32 s29, s23, s25
	v_readfirstlane_b32 s43, v142
	s_add_i32 s38, s29, 0x100
	s_mov_b32 m0, s43
	s_add_i32 s27, s27, 2
	buffer_load_dwordx4 v138, s[68:71], s38 offen lds
	s_barrier
	s_waitcnt lgkmcnt(0)
	s_setprio 1
	s_waitcnt lgkmcnt(3)
	v_mfma_f32_16x16x32_bf16 v[94:97], v[236:239], v[176:179], v[94:97]
	s_waitcnt lgkmcnt(1)
	v_mfma_f32_16x16x32_bf16 v[90:93], v[244:247], v[176:179], v[90:93]
	v_mfma_f32_16x16x32_bf16 v[86:89], v[236:239], v[184:187], v[86:89]
	v_mfma_f32_16x16x32_bf16 v[82:85], v[244:247], v[184:187], v[82:85]
	v_mfma_f32_16x16x32_bf16 v[78:81], v[236:239], v[192:195], v[78:81]
	v_mfma_f32_16x16x32_bf16 v[74:77], v[244:247], v[192:195], v[74:77]
	v_mfma_f32_16x16x32_bf16 v[70:73], v[236:239], v[200:203], v[70:73]
	v_mfma_f32_16x16x32_bf16 v[66:69], v[244:247], v[200:203], v[66:69]
	v_mfma_f32_16x16x32_bf16 v[94:97], v[240:243], v[180:183], v[94:97]
	s_waitcnt lgkmcnt(0)
	v_mfma_f32_16x16x32_bf16 v[90:93], v[248:251], v[180:183], v[90:93]
	v_mfma_f32_16x16x32_bf16 v[86:89], v[240:243], v[188:191], v[86:89]
	v_mfma_f32_16x16x32_bf16 v[82:85], v[248:251], v[188:191], v[82:85]
	v_mfma_f32_16x16x32_bf16 v[78:81], v[240:243], v[196:199], v[78:81]
	v_mfma_f32_16x16x32_bf16 v[74:77], v[248:251], v[196:199], v[74:77]
	v_mfma_f32_16x16x32_bf16 v[70:73], v[240:243], v[204:207], v[70:73]
	v_mfma_f32_16x16x32_bf16 v[66:69], v[248:251], v[204:207], v[66:69]
	s_setprio 0
	s_add_i32 s38, s22, s25
	v_readfirstlane_b32 s50, v139
	s_add_i32 s43, s38, 0x100
	s_mov_b32 m0, s50
	s_barrier
	ds_read_b128 v[176:179], v137 offset:16384
	ds_read_b128 v[180:183], v137 offset:17408
	ds_read_b128 v[184:187], v136 offset:16384
	ds_read_b128 v[188:191], v136 offset:17408
	ds_read_b128 v[192:195], v135 offset:16384
	ds_read_b128 v[196:199], v135 offset:17408
	ds_read_b128 v[200:203], v134 offset:16384
	ds_read_b128 v[204:207], v134 offset:17408
	buffer_load_dwordx4 v138, s[4:7], s43 offen lds
	s_add_i32 s43, s19, s25
	v_readfirstlane_b32 s51, v143
	s_add_i32 s50, s43, 0x100
	s_mov_b32 m0, s51
	s_nop 0
	buffer_load_dwordx4 v138, s[4:7], s50 offen lds
	s_barrier
	s_waitcnt lgkmcnt(0)
	s_setprio 1
	s_waitcnt lgkmcnt(7)
	v_mfma_f32_16x16x32_bf16 v[62:65], v[160:163], v[176:179], v[62:65]
	v_mfma_f32_16x16x32_bf16 v[58:61], v[168:171], v[176:179], v[58:61]
	s_waitcnt lgkmcnt(5)
	v_mfma_f32_16x16x32_bf16 v[54:57], v[160:163], v[184:187], v[54:57]
	v_mfma_f32_16x16x32_bf16 v[50:53], v[168:171], v[184:187], v[50:53]
	s_waitcnt lgkmcnt(3)
	v_mfma_f32_16x16x32_bf16 v[46:49], v[160:163], v[192:195], v[46:49]
	v_mfma_f32_16x16x32_bf16 v[42:45], v[168:171], v[192:195], v[42:45]
	s_waitcnt lgkmcnt(1)
	v_mfma_f32_16x16x32_bf16 v[38:41], v[160:163], v[200:203], v[38:41]
	v_mfma_f32_16x16x32_bf16 v[34:37], v[168:171], v[200:203], v[34:37]
	v_mfma_f32_16x16x32_bf16 v[62:65], v[164:167], v[180:183], v[62:65]
	v_mfma_f32_16x16x32_bf16 v[58:61], v[172:175], v[180:183], v[58:61]
	v_mfma_f32_16x16x32_bf16 v[54:57], v[164:167], v[188:191], v[54:57]
	v_mfma_f32_16x16x32_bf16 v[50:53], v[172:175], v[188:191], v[50:53]
	v_mfma_f32_16x16x32_bf16 v[46:49], v[164:167], v[196:199], v[46:49]
	v_mfma_f32_16x16x32_bf16 v[42:45], v[172:175], v[196:199], v[42:45]
	s_waitcnt lgkmcnt(0)
	v_mfma_f32_16x16x32_bf16 v[38:41], v[164:167], v[204:207], v[38:41]
	v_mfma_f32_16x16x32_bf16 v[34:37], v[172:175], v[204:207], v[34:37]
	s_setprio 0
	s_barrier
; #define WAIT_V(n) asm volatile("s_waitcnt vmcnt(" #n ")" ::: "memory")
; #define WAIT_L(n) asm volatile("s_waitcnt lgkmcnt(" #n ")" ::: "memory")
; #define BAR __builtin_amdgcn_s_barrier()
; #define SCHED __builtin_amdgcn_sched_barrier(0)
; template <int MODE>
; __device__ __forceinline__ void gemm_tile(const int ph, const int which, const int pm, const int pn) {
;     ...
;     WAIT_V(6); BAR; MMA(1, 1, At, B1); BAR;
;     LDB(B0, 1, 0); SCHED; LDA(At, 1, 0); STAGE(SA(0, 1), RA, brow + HALF, t + 2);
;     WAIT_L(8); BAR; WAIT_L(0); MMA(0, 0, At, B0); BAR; SCHED;
;     LDB(B1, 1, 1); STAGE(SB(1, 0), RB, bcol, t + 3);
;     BAR; WAIT_L(0); MMA(0, 1, At, B1); BAR;
;     LDA(At, 1, 1); STAGE(SA(1, 0), RA, brow, t + 3);
;     BAR; WAIT_L(0); MMA(1, 0, At, B0); BAR; SCHED;
	s_add_i32 s50, s18, s25
	v_readfirstlane_b32 s72, v144
	s_add_i32 s51, s50, 0x100
	s_mov_b32 m0, s72
	v_readfirstlane_b32 s73, v145
	buffer_load_dwordx4 v138, s[68:71], s51 offen lds
	s_add_i32 s51, s17, s25
	s_add_i32 s72, s51, 0x100
	s_mov_b32 m0, s73
	s_nop 0
	buffer_load_dwordx4 v138, s[68:71], s72 offen lds
	s_waitcnt vmcnt(6)
	s_barrier
	s_setprio 1
	v_mfma_f32_16x16x32_bf16 v[30:33], v[236:239], v[176:179], v[30:33]
	v_mfma_f32_16x16x32_bf16 v[26:29], v[244:247], v[176:179], v[26:29]
	v_mfma_f32_16x16x32_bf16 v[22:25], v[236:239], v[184:187], v[22:25]
	v_mfma_f32_16x16x32_bf16 v[18:21], v[244:247], v[184:187], v[18:21]
	v_mfma_f32_16x16x32_bf16 v[14:17], v[236:239], v[192:195], v[14:17]
	v_mfma_f32_16x16x32_bf16 v[10:13], v[244:247], v[192:195], v[10:13]
	v_mfma_f32_16x16x32_bf16 v[6:9], v[236:239], v[200:203], v[6:9]
	v_mfma_f32_16x16x32_bf16 v[2:5], v[244:247], v[200:203], v[2:5]
	v_mfma_f32_16x16x32_bf16 v[30:33], v[240:243], v[180:183], v[30:33]
	v_mfma_f32_16x16x32_bf16 v[26:29], v[248:251], v[180:183], v[26:29]
	v_mfma_f32_16x16x32_bf16 v[22:25], v[240:243], v[188:191], v[22:25]
	v_mfma_f32_16x16x32_bf16 v[18:21], v[248:251], v[188:191], v[18:21]
	v_mfma_f32_16x16x32_bf16 v[14:17], v[240:243], v[196:199], v[14:17]
	v_mfma_f32_16x16x32_bf16 v[10:13], v[248:251], v[196:199], v[10:13]
	v_mfma_f32_16x16x32_bf16 v[6:9], v[240:243], v[204:207], v[6:9]
	v_mfma_f32_16x16x32_bf16 v[2:5], v[248:251], v[204:207], v[2:5]
	s_setprio 0
	s_barrier
	ds_read_b128 v[160:163], v146
	ds_read_b128 v[164:167], v146 offset:1024
	ds_read_b128 v[168:171], v146 offset:2048
	ds_read_b128 v[172:175], v146 offset:3072
	v_readfirstlane_b32 s72, v147
	s_addk_i32 s12, 0x100
	s_mov_b32 m0, s72
	ds_read_b128 v[176:179], v137 offset:32768
	ds_read_b128 v[180:183], v137 offset:33792
	ds_read_b128 v[184:187], v136 offset:32768
	ds_read_b128 v[188:191], v136 offset:33792
	ds_read_b128 v[192:195], v135 offset:32768
	ds_read_b128 v[196:199], v135 offset:33792
	ds_read_b128 v[200:203], v134 offset:32768
	ds_read_b128 v[204:207], v134 offset:33792
	buffer_load_dwordx4 v138, s[4:7], s12 offen lds
	v_readfirstlane_b32 s12, v148
	s_addk_i32 s13, 0x100
	s_mov_b32 m0, s12
	s_nop 0
	buffer_load_dwordx4 v138, s[4:7], s13 offen lds
	s_waitcnt lgkmcnt(8)
	s_barrier
	s_waitcnt lgkmcnt(0)
	s_setprio 1
	s_waitcnt lgkmcnt(7)
	v_mfma_f32_16x16x32_bf16 v[126:129], v[160:163], v[176:179], v[126:129]
	v_mfma_f32_16x16x32_bf16 v[122:125], v[168:171], v[176:179], v[122:125]
	s_waitcnt lgkmcnt(5)
	v_mfma_f32_16x16x32_bf16 v[118:121], v[160:163], v[184:187], v[118:121]
	v_mfma_f32_16x16x32_bf16 v[114:117], v[168:171], v[184:187], v[114:117]
	s_waitcnt lgkmcnt(3)
	v_mfma_f32_16x16x32_bf16 v[110:113], v[160:163], v[192:195], v[110:113]
	v_mfma_f32_16x16x32_bf16 v[106:109], v[168:171], v[192:195], v[106:109]
	s_waitcnt lgkmcnt(1)
	v_mfma_f32_16x16x32_bf16 v[102:105], v[160:163], v[200:203], v[102:105]
	v_mfma_f32_16x16x32_bf16 v[98:101], v[168:171], v[200:203], v[98:101]
	v_mfma_f32_16x16x32_bf16 v[126:129], v[164:167], v[180:183], v[126:129]
	v_mfma_f32_16x16x32_bf16 v[122:125], v[172:175], v[180:183], v[122:125]
	v_mfma_f32_16x16x32_bf16 v[118:121], v[164:167], v[188:191], v[118:121]
	v_mfma_f32_16x16x32_bf16 v[114:117], v[172:175], v[188:191], v[114:117]
	v_mfma_f32_16x16x32_bf16 v[110:113], v[164:167], v[196:199], v[110:113]
	v_mfma_f32_16x16x32_bf16 v[106:109], v[172:175], v[196:199], v[106:109]
	s_waitcnt lgkmcnt(0)
	v_mfma_f32_16x16x32_bf16 v[102:105], v[164:167], v[204:207], v[102:105]
	v_mfma_f32_16x16x32_bf16 v[98:101], v[172:175], v[204:207], v[98:101]
	s_setprio 0
	s_barrier
	v_readfirstlane_b32 s12, v149
	s_addk_i32 s28, 0x180
	s_mov_b32 m0, s12
	v_readfirstlane_b32 s12, v150
	ds_read_b128 v[236:239], v140
	ds_read_b128 v[240:243], v140 offset:1024
	ds_read_b128 v[244:247], v140 offset:2048
	ds_read_b128 v[248:251], v140 offset:3072
	buffer_load_dwordx4 v138, s[68:71], s28 offen lds
	s_addk_i32 s29, 0x180
	s_mov_b32 m0, s12
	s_nop 0
	buffer_load_dwordx4 v138, s[68:71], s29 offen lds
	s_barrier
	s_waitcnt lgkmcnt(0)
	s_setprio 1
	s_waitcnt lgkmcnt(3)
	v_mfma_f32_16x16x32_bf16 v[94:97], v[236:239], v[176:179], v[94:97]
	s_waitcnt lgkmcnt(1)
	v_mfma_f32_16x16x32_bf16 v[90:93], v[244:247], v[176:179], v[90:93]
	v_mfma_f32_16x16x32_bf16 v[86:89], v[236:239], v[184:187], v[86:89]
	v_mfma_f32_16x16x32_bf16 v[82:85], v[244:247], v[184:187], v[82:85]
	v_mfma_f32_16x16x32_bf16 v[78:81], v[236:239], v[192:195], v[78:81]
	v_mfma_f32_16x16x32_bf16 v[74:77], v[244:247], v[192:195], v[74:77]
	v_mfma_f32_16x16x32_bf16 v[70:73], v[236:239], v[200:203], v[70:73]
	v_mfma_f32_16x16x32_bf16 v[66:69], v[244:247], v[200:203], v[66:69]
	v_mfma_f32_16x16x32_bf16 v[94:97], v[240:243], v[180:183], v[94:97]
	s_waitcnt lgkmcnt(0)
	v_mfma_f32_16x16x32_bf16 v[90:93], v[248:251], v[180:183], v[90:93]
	v_mfma_f32_16x16x32_bf16 v[86:89], v[240:243], v[188:191], v[86:89]
	v_mfma_f32_16x16x32_bf16 v[82:85], v[248:251], v[188:191], v[82:85]
	v_mfma_f32_16x16x32_bf16 v[78:81], v[240:243], v[196:199], v[78:81]
	v_mfma_f32_16x16x32_bf16 v[74:77], v[248:251], v[196:199], v[74:77]
	v_mfma_f32_16x16x32_bf16 v[70:73], v[240:243], v[204:207], v[70:73]
	v_mfma_f32_16x16x32_bf16 v[66:69], v[248:251], v[204:207], v[66:69]
	s_setprio 0
	v_readfirstlane_b32 s12, v151
	s_addk_i32 s38, 0x180
	s_mov_b32 m0, s12
	v_readfirstlane_b32 s12, v152
	s_barrier
	ds_read_b128 v[176:179], v137 offset:49152
	ds_read_b128 v[180:183], v137 offset:50176
	ds_read_b128 v[184:187], v136 offset:49152
	ds_read_b128 v[188:191], v136 offset:50176
	ds_read_b128 v[192:195], v135 offset:49152
	ds_read_b128 v[196:199], v135 offset:50176
	ds_read_b128 v[200:203], v134 offset:49152
	ds_read_b128 v[204:207], v134 offset:50176
	buffer_load_dwordx4 v138, s[4:7], s38 offen lds
	s_addk_i32 s43, 0x180
	s_mov_b32 m0, s12
	s_nop 0
	buffer_load_dwordx4 v138, s[4:7], s43 offen lds
	s_barrier
; #define WAIT_V(n) asm volatile("s_waitcnt vmcnt(" #n ")" ::: "memory")
; #define WAIT_L(n) asm volatile("s_waitcnt lgkmcnt(" #n ")" ::: "memory")
; #define BAR __builtin_amdgcn_s_barrier()
; #define SCHED __builtin_amdgcn_sched_barrier(0)
; template <int MODE>
; __device__ __forceinline__ void gemm_tile(const int ph, const int which, const int pm, const int pn) {
;     ...
;     BAR; WAIT_L(0); MMA(1, 0, At, B0); BAR; SCHED;
;     STAGE(SB(1, 1), RB, bcolB, t + 3);
;     WAIT_V(6); BAR; MMA(1, 1, At, B1); BAR;
;   }
;   {
;     LDB(B0, 0, 0); LDA(At, 0, 0); STAGE(SA(1, 1), RA, brow + HALF, nt - 1);
;     BAR; WAIT_L(0); MMA(0, 0, At, B0); BAR;
	s_waitcnt lgkmcnt(0)
	s_setprio 1
	s_waitcnt lgkmcnt(7)
	v_mfma_f32_16x16x32_bf16 v[62:65], v[160:163], v[176:179], v[62:65]
	v_mfma_f32_16x16x32_bf16 v[58:61], v[168:171], v[176:179], v[58:61]
	s_waitcnt lgkmcnt(5)
	v_mfma_f32_16x16x32_bf16 v[54:57], v[160:163], v[184:187], v[54:57]
	v_mfma_f32_16x16x32_bf16 v[50:53], v[168:171], v[184:187], v[50:53]
	s_waitcnt lgkmcnt(3)
	v_mfma_f32_16x16x32_bf16 v[46:49], v[160:163], v[192:195], v[46:49]
	v_mfma_f32_16x16x32_bf16 v[42:45], v[168:171], v[192:195], v[42:45]
	s_waitcnt lgkmcnt(1)
	v_mfma_f32_16x16x32_bf16 v[38:41], v[160:163], v[200:203], v[38:41]
	v_mfma_f32_16x16x32_bf16 v[34:37], v[168:171], v[200:203], v[34:37]
	v_mfma_f32_16x16x32_bf16 v[62:65], v[164:167], v[180:183], v[62:65]
	v_mfma_f32_16x16x32_bf16 v[58:61], v[172:175], v[180:183], v[58:61]
	v_mfma_f32_16x16x32_bf16 v[54:57], v[164:167], v[188:191], v[54:57]
	v_mfma_f32_16x16x32_bf16 v[50:53], v[172:175], v[188:191], v[50:53]
	v_mfma_f32_16x16x32_bf16 v[46:49], v[164:167], v[196:199], v[46:49]
	v_mfma_f32_16x16x32_bf16 v[42:45], v[172:175], v[196:199], v[42:45]
	s_waitcnt lgkmcnt(0)
	v_mfma_f32_16x16x32_bf16 v[38:41], v[164:167], v[204:207], v[38:41]
	v_mfma_f32_16x16x32_bf16 v[34:37], v[172:175], v[204:207], v[34:37]
	s_setprio 0
	s_barrier
	v_readfirstlane_b32 s12, v154
	s_addk_i32 s50, 0x180
	s_mov_b32 m0, s12
	v_readfirstlane_b32 s12, v156
	buffer_load_dwordx4 v138, s[68:71], s50 offen lds
	s_addk_i32 s51, 0x180
	s_mov_b32 m0, s12
	s_nop 0
	buffer_load_dwordx4 v138, s[68:71], s51 offen lds
	s_waitcnt vmcnt(6)
	s_barrier
	s_setprio 1
	v_mfma_f32_16x16x32_bf16 v[30:33], v[236:239], v[176:179], v[30:33]
	v_mfma_f32_16x16x32_bf16 v[26:29], v[244:247], v[176:179], v[26:29]
	v_mfma_f32_16x16x32_bf16 v[22:25], v[236:239], v[184:187], v[22:25]
	v_mfma_f32_16x16x32_bf16 v[18:21], v[244:247], v[184:187], v[18:21]
	v_mfma_f32_16x16x32_bf16 v[14:17], v[236:239], v[192:195], v[14:17]
	v_mfma_f32_16x16x32_bf16 v[10:13], v[244:247], v[192:195], v[10:13]
	v_mfma_f32_16x16x32_bf16 v[6:9], v[236:239], v[200:203], v[6:9]
	v_mfma_f32_16x16x32_bf16 v[2:5], v[244:247], v[200:203], v[2:5]
	v_mfma_f32_16x16x32_bf16 v[30:33], v[240:243], v[180:183], v[30:33]
	v_mfma_f32_16x16x32_bf16 v[26:29], v[248:251], v[180:183], v[26:29]
	v_mfma_f32_16x16x32_bf16 v[22:25], v[240:243], v[188:191], v[22:25]
	v_mfma_f32_16x16x32_bf16 v[18:21], v[248:251], v[188:191], v[18:21]
	v_mfma_f32_16x16x32_bf16 v[14:17], v[240:243], v[196:199], v[14:17]
	v_mfma_f32_16x16x32_bf16 v[10:13], v[248:251], v[196:199], v[10:13]
	v_mfma_f32_16x16x32_bf16 v[6:9], v[240:243], v[204:207], v[6:9]
	v_mfma_f32_16x16x32_bf16 v[2:5], v[248:251], v[204:207], v[2:5]
	s_setprio 0
	s_addk_i32 s25, 0x100
	s_cmp_lt_u32 s27, s2
	s_cbranch_scc1 .Lgemm_head_131
	s_barrier
	s_add_i32 s2, s26, s11
	s_lshl_b32 s2, s2, 1
	v_readfirstlane_b32 s3, v155
	s_addk_i32 s2, 0xff80
	s_mov_b32 s6, s70
	s_mov_b32 s7, s71
	s_mov_b32 m0, s3
	v_readfirstlane_b32 s3, v153
	ds_read_b128 v[142:145], v158
	ds_read_b128 v[148:151], v158 offset:1024
	ds_read_b128 v[160:163], v158 offset:2048
	ds_read_b128 v[164:167], v158 offset:3072
	ds_read_b128 v[168:171], v137
	ds_read_b128 v[172:175], v137 offset:1024
	ds_read_b128 v[176:179], v136
	ds_read_b128 v[180:183], v136 offset:1024
	ds_read_b128 v[184:187], v135
	ds_read_b128 v[188:191], v135 offset:1024
	ds_read_b128 v[192:195], v134
	ds_read_b128 v[196:199], v134 offset:1024
	buffer_load_dwordx4 v138, s[4:7], s2 offen lds
	s_add_i32 s2, s2, s10
	s_mov_b32 m0, s3
	s_nop 0
	buffer_load_dwordx4 v138, s[4:7], s2 offen lds
	s_barrier
	s_waitcnt lgkmcnt(0)
	s_setprio 1
	s_waitcnt lgkmcnt(7)
	v_mfma_f32_16x16x32_bf16 v[126:129], v[142:145], v[168:171], v[126:129]
	v_mfma_f32_16x16x32_bf16 v[122:125], v[160:163], v[168:171], v[122:125]
	s_waitcnt lgkmcnt(5)
	v_mfma_f32_16x16x32_bf16 v[118:121], v[142:145], v[176:179], v[118:121]
	v_mfma_f32_16x16x32_bf16 v[114:117], v[160:163], v[176:179], v[114:117]
	s_waitcnt lgkmcnt(1)
	v_mfma_f32_16x16x32_bf16 v[102:105], v[142:145], v[192:195], v[102:105]
	v_mfma_f32_16x16x32_bf16 v[98:101], v[160:163], v[192:195], v[98:101]
	v_mfma_f32_16x16x32_bf16 v[126:129], v[148:151], v[172:175], v[126:129]
	v_mfma_f32_16x16x32_bf16 v[122:125], v[164:167], v[172:175], v[122:125]
	v_mfma_f32_16x16x32_bf16 v[118:121], v[148:151], v[180:183], v[118:121]
	v_mfma_f32_16x16x32_bf16 v[114:117], v[164:167], v[180:183], v[114:117]
	v_mfma_f32_16x16x32_bf16 v[110:113], v[142:145], v[184:187], v[110:113]
	v_mfma_f32_16x16x32_bf16 v[106:109], v[160:163], v[184:187], v[106:109]
	s_waitcnt lgkmcnt(0)
	v_mfma_f32_16x16x32_bf16 v[102:105], v[148:151], v[196:199], v[102:105]
	v_mfma_f32_16x16x32_bf16 v[98:101], v[164:167], v[196:199], v[98:101]
	v_mfma_f32_16x16x32_bf16 v[152:155], v[148:151], v[188:191], v[110:113]
	v_mfma_f32_16x16x32_bf16 v[200:203], v[164:167], v[188:191], v[106:109]
	s_setprio 0
	s_barrier
	s_nop 0
	ds_read_b128 v[106:109], v157
	ds_read_b128 v[110:113], v157 offset:1024
	ds_read_b128 v[204:207], v157 offset:2048
	ds_read_b128 v[156:159], v157 offset:3072
	s_barrier
; #define WAIT_V(n) asm volatile("s_waitcnt vmcnt(" #n ")" ::: "memory")
; #define WAIT_L(n) asm volatile("s_waitcnt lgkmcnt(" #n ")" ::: "memory")
; #define BAR __builtin_amdgcn_s_barrier()
; template <int MODE>
; __device__ __forceinline__ void gemm_tile(const int ph, const int which, const int pm, const int pn) {
;     ...
;     BAR; WAIT_L(0); MMA(0, 0, At, B0); BAR;
;     LDB(B1, 0, 1); BAR; WAIT_L(0); MMA(0, 1, At, B1); BAR;
;     LDA(At, 0, 1); WAIT_V(4); BAR; WAIT_L(0); MMA(1, 0, At, B0); MMA(1, 1, At, B1); BAR;
;   }
;   {
;     LDB(B0, 1, 0); LDA(At, 1, 0); WAIT_V(2); BAR; WAIT_L(0); MMA(0, 0, At, B0); BAR;
	s_waitcnt lgkmcnt(0)
	s_setprio 1
	s_waitcnt lgkmcnt(3)
	v_mfma_f32_16x16x32_bf16 v[86:89], v[106:109], v[176:179], v[86:89]
	s_waitcnt lgkmcnt(1)
	v_mfma_f32_16x16x32_bf16 v[82:85], v[204:207], v[176:179], v[82:85]
	v_mfma_f32_16x16x32_bf16 v[70:73], v[106:109], v[192:195], v[70:73]
	v_mfma_f32_16x16x32_bf16 v[66:69], v[204:207], v[192:195], v[66:69]
	v_mfma_f32_16x16x32_bf16 v[94:97], v[106:109], v[168:171], v[94:97]
	v_mfma_f32_16x16x32_bf16 v[90:93], v[204:207], v[168:171], v[90:93]
	v_mfma_f32_16x16x32_bf16 v[86:89], v[110:113], v[180:183], v[86:89]
	s_waitcnt lgkmcnt(0)
	v_mfma_f32_16x16x32_bf16 v[82:85], v[156:159], v[180:183], v[82:85]
	v_mfma_f32_16x16x32_bf16 v[78:81], v[106:109], v[184:187], v[78:81]
	v_mfma_f32_16x16x32_bf16 v[74:77], v[204:207], v[184:187], v[74:77]
	v_mfma_f32_16x16x32_bf16 v[70:73], v[110:113], v[196:199], v[70:73]
	v_mfma_f32_16x16x32_bf16 v[66:69], v[156:159], v[196:199], v[66:69]
	v_mfma_f32_16x16x32_bf16 v[236:239], v[110:113], v[172:175], v[94:97]
	v_mfma_f32_16x16x32_bf16 v[168:171], v[156:159], v[172:175], v[90:93]
	v_mfma_f32_16x16x32_bf16 v[172:175], v[110:113], v[188:191], v[78:81]
	v_mfma_f32_16x16x32_bf16 v[176:179], v[156:159], v[188:191], v[74:77]
	s_setprio 0
	s_barrier
	s_nop 0
	ds_read_b128 v[74:77], v137 offset:16384
	ds_read_b128 v[78:81], v137 offset:17408
	ds_read_b128 v[90:93], v136 offset:16384
	ds_read_b128 v[94:97], v136 offset:17408
	ds_read_b128 v[180:183], v135 offset:16384
	ds_read_b128 v[184:187], v135 offset:17408
	ds_read_b128 v[188:191], v134 offset:16384
	ds_read_b128 v[192:195], v134 offset:17408
	s_waitcnt vmcnt(4)
	s_barrier
	s_waitcnt lgkmcnt(0)
	s_setprio 1
	s_waitcnt lgkmcnt(7)
	v_mfma_f32_16x16x32_bf16 v[62:65], v[142:145], v[74:77], v[62:65]
	v_mfma_f32_16x16x32_bf16 v[58:61], v[160:163], v[74:77], v[58:61]
	s_waitcnt lgkmcnt(5)
	v_mfma_f32_16x16x32_bf16 v[54:57], v[142:145], v[90:93], v[54:57]
	v_mfma_f32_16x16x32_bf16 v[50:53], v[160:163], v[90:93], v[50:53]
	s_waitcnt lgkmcnt(1)
	v_mfma_f32_16x16x32_bf16 v[38:41], v[142:145], v[188:191], v[38:41]
	v_mfma_f32_16x16x32_bf16 v[34:37], v[160:163], v[188:191], v[34:37]
	v_mfma_f32_16x16x32_bf16 v[62:65], v[148:151], v[78:81], v[62:65]
	v_mfma_f32_16x16x32_bf16 v[58:61], v[164:167], v[78:81], v[58:61]
	v_mfma_f32_16x16x32_bf16 v[54:57], v[148:151], v[94:97], v[54:57]
	v_mfma_f32_16x16x32_bf16 v[50:53], v[164:167], v[94:97], v[50:53]
	v_mfma_f32_16x16x32_bf16 v[46:49], v[142:145], v[180:183], v[46:49]
	v_mfma_f32_16x16x32_bf16 v[42:45], v[160:163], v[180:183], v[42:45]
	s_waitcnt lgkmcnt(0)
	v_mfma_f32_16x16x32_bf16 v[38:41], v[148:151], v[192:195], v[38:41]
	v_mfma_f32_16x16x32_bf16 v[34:37], v[164:167], v[192:195], v[34:37]
	v_mfma_f32_16x16x32_bf16 v[196:199], v[148:151], v[184:187], v[46:49]
	v_mfma_f32_16x16x32_bf16 v[240:243], v[164:167], v[184:187], v[42:45]
	v_mfma_f32_16x16x32_bf16 v[22:25], v[106:109], v[90:93], v[22:25]
	v_mfma_f32_16x16x32_bf16 v[18:21], v[204:207], v[90:93], v[18:21]
	v_mfma_f32_16x16x32_bf16 v[6:9], v[106:109], v[188:191], v[6:9]
	v_mfma_f32_16x16x32_bf16 v[2:5], v[204:207], v[188:191], v[2:5]
	v_mfma_f32_16x16x32_bf16 v[30:33], v[106:109], v[74:77], v[30:33]
	v_mfma_f32_16x16x32_bf16 v[26:29], v[204:207], v[74:77], v[26:29]
	v_mfma_f32_16x16x32_bf16 v[22:25], v[110:113], v[94:97], v[22:25]
	v_mfma_f32_16x16x32_bf16 v[18:21], v[156:159], v[94:97], v[18:21]
	v_mfma_f32_16x16x32_bf16 v[14:17], v[106:109], v[180:183], v[14:17]
	v_mfma_f32_16x16x32_bf16 v[10:13], v[204:207], v[180:183], v[10:13]
	v_mfma_f32_16x16x32_bf16 v[6:9], v[110:113], v[192:195], v[6:9]
	v_mfma_f32_16x16x32_bf16 v[2:5], v[156:159], v[192:195], v[2:5]
	v_mfma_f32_16x16x32_bf16 v[142:145], v[110:113], v[78:81], v[30:33]
	v_mfma_f32_16x16x32_bf16 v[148:151], v[156:159], v[78:81], v[26:29]
	v_mfma_f32_16x16x32_bf16 v[160:163], v[110:113], v[184:187], v[14:17]
	v_mfma_f32_16x16x32_bf16 v[164:167], v[156:159], v[184:187], v[10:13]
	s_setprio 0
	s_barrier
	s_nop 0
	ds_read_b128 v[10:13], v146
	ds_read_b128 v[14:17], v146 offset:1024
	ds_read_b128 v[156:159], v146 offset:2048
	ds_read_b128 v[180:183], v146 offset:3072
	ds_read_b128 v[26:29], v137 offset:32768
	ds_read_b128 v[30:33], v137 offset:33792
	ds_read_b128 v[42:45], v136 offset:32768
	ds_read_b128 v[46:49], v136 offset:33792
	ds_read_b128 v[184:187], v135 offset:32768
	ds_read_b128 v[188:191], v135 offset:33792
	ds_read_b128 v[192:195], v134 offset:32768
	ds_read_b128 v[204:207], v134 offset:33792
	s_waitcnt vmcnt(2)
	s_barrier
; #define WAIT_V(n) asm volatile("s_waitcnt vmcnt(" #n ")" ::: "memory")
; #define WAIT_L(n) asm volatile("s_waitcnt lgkmcnt(" #n ")" ::: "memory")
; #define BAR __builtin_amdgcn_s_barrier()
; template <int MODE>
; __device__ __forceinline__ void gemm_tile(const int ph, const int which, const int pm, const int pn) {
;     ...
;     LDB(B0, 1, 0); LDA(At, 1, 0); WAIT_V(2); BAR; WAIT_L(0); MMA(0, 0, At, B0); BAR;
;     LDB(B1, 1, 1); WAIT_V(0); BAR; WAIT_L(0); MMA(0, 1, At, B1); BAR;
;     LDA(At, 1, 1); BAR; WAIT_L(0); MMA(1, 0, At, B0); MMA(1, 1, At, B1); BAR;
;   }
;   if (wr == 0) BAR;
	s_waitcnt lgkmcnt(0)
	s_setprio 1
	s_waitcnt lgkmcnt(7)
	v_mfma_f32_16x16x32_bf16 v[74:77], v[10:13], v[26:29], v[126:129]
	s_waitcnt lgkmcnt(6)
	v_mfma_f32_16x16x32_bf16 v[126:129], v[14:17], v[30:33], v[74:77]
	v_mfma_f32_16x16x32_bf16 v[74:77], v[156:159], v[26:29], v[122:125]
	v_mfma_f32_16x16x32_bf16 v[122:125], v[180:183], v[30:33], v[74:77]
	s_waitcnt lgkmcnt(5)
	v_mfma_f32_16x16x32_bf16 v[74:77], v[10:13], v[42:45], v[118:121]
	s_waitcnt lgkmcnt(4)
	v_mfma_f32_16x16x32_bf16 v[110:113], v[14:17], v[46:49], v[74:77]
	v_mfma_f32_16x16x32_bf16 v[74:77], v[156:159], v[42:45], v[114:117]
	v_mfma_f32_16x16x32_bf16 v[106:109], v[180:183], v[46:49], v[74:77]
	s_waitcnt lgkmcnt(3)
	v_mfma_f32_16x16x32_bf16 v[74:77], v[10:13], v[184:187], v[152:155]
	s_waitcnt lgkmcnt(2)
	v_mfma_f32_16x16x32_bf16 v[94:97], v[14:17], v[188:191], v[74:77]
	v_mfma_f32_16x16x32_bf16 v[74:77], v[156:159], v[184:187], v[200:203]
	v_mfma_f32_16x16x32_bf16 v[90:93], v[180:183], v[188:191], v[74:77]
	s_waitcnt lgkmcnt(1)
	v_mfma_f32_16x16x32_bf16 v[74:77], v[10:13], v[192:195], v[102:105]
	s_waitcnt lgkmcnt(0)
	v_mfma_f32_16x16x32_bf16 v[78:81], v[14:17], v[204:207], v[74:77]
	v_mfma_f32_16x16x32_bf16 v[74:77], v[156:159], v[192:195], v[98:101]
	v_mfma_f32_16x16x32_bf16 v[74:77], v[180:183], v[204:207], v[74:77]
	s_setprio 0
	s_barrier
	ds_read_b128 v[152:155], v140
	ds_read_b128 v[200:203], v140 offset:1024
	ds_read_b128 v[244:247], v140 offset:2048
	ds_read_b128 v[138:141], v140 offset:3072
	s_waitcnt vmcnt(0)
	s_barrier
	s_waitcnt lgkmcnt(0)
	s_setprio 1
	s_waitcnt lgkmcnt(3)
	v_mfma_f32_16x16x32_bf16 v[98:101], v[152:155], v[26:29], v[236:239]
	s_waitcnt lgkmcnt(1)
	v_mfma_f32_16x16x32_bf16 v[26:29], v[244:247], v[26:29], v[168:171]
	s_waitcnt lgkmcnt(0)
	v_mfma_f32_16x16x32_bf16 v[114:117], v[138:141], v[30:33], v[26:29]
	v_mfma_f32_16x16x32_bf16 v[26:29], v[152:155], v[42:45], v[86:89]
	v_mfma_f32_16x16x32_bf16 v[102:105], v[200:203], v[46:49], v[26:29]
	v_mfma_f32_16x16x32_bf16 v[26:29], v[244:247], v[42:45], v[82:85]
	v_mfma_f32_16x16x32_bf16 v[118:121], v[200:203], v[30:33], v[98:101]
	v_mfma_f32_16x16x32_bf16 v[98:101], v[138:141], v[46:49], v[26:29]
	v_mfma_f32_16x16x32_bf16 v[26:29], v[152:155], v[184:187], v[172:175]
	v_mfma_f32_16x16x32_bf16 v[86:89], v[200:203], v[188:191], v[26:29]
	v_mfma_f32_16x16x32_bf16 v[26:29], v[244:247], v[184:187], v[176:179]
	v_mfma_f32_16x16x32_bf16 v[82:85], v[138:141], v[188:191], v[26:29]
	v_mfma_f32_16x16x32_bf16 v[26:29], v[152:155], v[192:195], v[70:73]
	v_mfma_f32_16x16x32_bf16 v[70:73], v[200:203], v[204:207], v[26:29]
	v_mfma_f32_16x16x32_bf16 v[26:29], v[244:247], v[192:195], v[66:69]
	v_mfma_f32_16x16x32_bf16 v[66:69], v[138:141], v[204:207], v[26:29]
	s_setprio 0
	s_barrier
	ds_read_b128 v[168:171], v137 offset:49152
	ds_read_b128 v[172:175], v137 offset:50176
	ds_read_b128 v[176:179], v136 offset:49152
	ds_read_b128 v[184:187], v136 offset:50176
	ds_read_b128 v[188:191], v135 offset:49152
	ds_read_b128 v[192:195], v135 offset:50176
	ds_read_b128 v[204:207], v134 offset:49152
	ds_read_b128 v[134:137], v134 offset:50176
	s_barrier
	s_waitcnt lgkmcnt(0)
	s_setprio 1
	s_waitcnt lgkmcnt(7)
	v_mfma_f32_16x16x32_bf16 v[26:29], v[10:13], v[168:171], v[62:65]
	s_waitcnt lgkmcnt(6)
	v_mfma_f32_16x16x32_bf16 v[62:65], v[14:17], v[172:175], v[26:29]
	v_mfma_f32_16x16x32_bf16 v[26:29], v[156:159], v[168:171], v[58:61]
	v_mfma_f32_16x16x32_bf16 v[58:61], v[180:183], v[172:175], v[26:29]
	s_waitcnt lgkmcnt(5)
	v_mfma_f32_16x16x32_bf16 v[26:29], v[10:13], v[176:179], v[54:57]
	s_waitcnt lgkmcnt(4)
	v_mfma_f32_16x16x32_bf16 v[46:49], v[14:17], v[184:187], v[26:29]
	v_mfma_f32_16x16x32_bf16 v[26:29], v[156:159], v[176:179], v[50:53]
	v_mfma_f32_16x16x32_bf16 v[42:45], v[180:183], v[184:187], v[26:29]
	s_waitcnt lgkmcnt(3)
	v_mfma_f32_16x16x32_bf16 v[26:29], v[10:13], v[188:191], v[196:199]
	s_waitcnt lgkmcnt(1)
	v_mfma_f32_16x16x32_bf16 v[10:13], v[10:13], v[204:207], v[38:41]
	v_mfma_f32_16x16x32_bf16 v[30:33], v[14:17], v[192:195], v[26:29]
	v_mfma_f32_16x16x32_bf16 v[26:29], v[156:159], v[188:191], v[240:243]
	s_waitcnt lgkmcnt(0)
	v_mfma_f32_16x16x32_bf16 v[14:17], v[14:17], v[134:137], v[10:13]
	v_mfma_f32_16x16x32_bf16 v[10:13], v[156:159], v[204:207], v[34:37]
	v_mfma_f32_16x16x32_bf16 v[26:29], v[180:183], v[192:195], v[26:29]
	v_mfma_f32_16x16x32_bf16 v[10:13], v[180:183], v[134:137], v[10:13]
	v_mfma_f32_16x16x32_bf16 v[34:37], v[152:155], v[168:171], v[142:145]
	v_mfma_f32_16x16x32_bf16 v[54:57], v[200:203], v[172:175], v[34:37]
	v_mfma_f32_16x16x32_bf16 v[34:37], v[244:247], v[168:171], v[148:151]
	v_mfma_f32_16x16x32_bf16 v[18:21], v[244:247], v[176:179], v[18:21]
	v_mfma_f32_16x16x32_bf16 v[50:53], v[138:141], v[172:175], v[34:37]
	v_mfma_f32_16x16x32_bf16 v[22:25], v[152:155], v[176:179], v[22:25]
	v_mfma_f32_16x16x32_bf16 v[34:37], v[138:141], v[184:187], v[18:21]
	v_mfma_f32_16x16x32_bf16 v[18:21], v[152:155], v[188:191], v[160:163]
	v_mfma_f32_16x16x32_bf16 v[38:41], v[200:203], v[184:187], v[22:25]
	v_mfma_f32_16x16x32_bf16 v[22:25], v[200:203], v[192:195], v[18:21]
	v_mfma_f32_16x16x32_bf16 v[18:21], v[244:247], v[188:191], v[164:167]
	v_mfma_f32_16x16x32_bf16 v[6:9], v[152:155], v[204:207], v[6:9]
	v_mfma_f32_16x16x32_bf16 v[2:5], v[244:247], v[204:207], v[2:5]
	v_mfma_f32_16x16x32_bf16 v[18:21], v[138:141], v[192:195], v[18:21]
	v_mfma_f32_16x16x32_bf16 v[6:9], v[200:203], v[134:137], v[6:9]
	v_mfma_f32_16x16x32_bf16 v[2:5], v[138:141], v[134:137], v[2:5]
	s_setprio 0
	s_movk_i32 s2, 0x100
	v_cmp_gt_u32_e32 vcc, s2, v0
	s_barrier
	s_and_saveexec_b64 s[2:3], vcc
	s_cbranch_execz .LBB0_134
	s_barrier

; #define WAIT_L(n) asm volatile("s_waitcnt lgkmcnt(" #n ")" ::: "memory")
; #define BAR __builtin_amdgcn_s_barrier()
; #define SCHED __builtin_amdgcn_sched_barrier(0)
; template <int MODE>
; __device__ __forceinline__ void gemm_tile(const int ph, const int which, const int pm, const int pn) {
;     ...
;     LDB(B0, 0, 0); SCHED; LDA(At, 0, 0); STAGE(SA(1, 1), RA, brow + HALF, t + 1);
;     WAIT_L(8); BAR; WAIT_L(0); MMA(0, 0, At, B0); BAR; SCHED;
;     LDB(B1, 0, 1); STAGE(SB(0, 0), RB, bcol, t + 2);
;     BAR; WAIT_L(0); MMA(0, 1, At, B1); BAR;
;     LDA(At, 0, 1); STAGE(SA(0, 0), RA, brow, t + 2);
;     BAR; WAIT_L(0); MMA(1, 0, At, B0); BAR; SCHED;
.LBB0_218:
	ds_read_b128 v[158:161], v156
	ds_read_b128 v[162:165], v156 offset:1024
	ds_read_b128 v[166:169], v156 offset:2048
	ds_read_b128 v[170:173], v156 offset:3072
	s_add_i32 s12, s18, s27
	v_readfirstlane_b32 s29, v153
	s_add_i32 s13, s12, 0x80
	s_mov_b32 m0, s29
	ds_read_b128 v[174:177], v134
	ds_read_b128 v[178:181], v134 offset:1024
	ds_read_b128 v[182:185], v133
	ds_read_b128 v[186:189], v133 offset:1024
	ds_read_b128 v[190:193], v132
	ds_read_b128 v[194:197], v132 offset:1024
	ds_read_b128 v[198:201], v131
	ds_read_b128 v[202:205], v131 offset:1024
	buffer_load_dwordx4 v135, s[4:7], s13 offen lds
	s_add_i32 s13, s17, s27
	v_readfirstlane_b32 s38, v151
	s_add_i32 s29, s13, 0x80
	s_mov_b32 m0, s38
	s_nop 0
	buffer_load_dwordx4 v135, s[4:7], s29 offen lds
	s_waitcnt lgkmcnt(8)
	s_barrier
	s_waitcnt lgkmcnt(0)
	s_setprio 1
	s_waitcnt lgkmcnt(7)
	v_mfma_f32_16x16x32_bf16 v[126:129], v[158:161], v[174:177], v[126:129]
	v_mfma_f32_16x16x32_bf16 v[122:125], v[166:169], v[174:177], v[122:125]
	s_waitcnt lgkmcnt(5)
	v_mfma_f32_16x16x32_bf16 v[118:121], v[158:161], v[182:185], v[118:121]
	v_mfma_f32_16x16x32_bf16 v[114:117], v[166:169], v[182:185], v[114:117]
	s_waitcnt lgkmcnt(3)
	v_mfma_f32_16x16x32_bf16 v[110:113], v[158:161], v[190:193], v[110:113]
	v_mfma_f32_16x16x32_bf16 v[106:109], v[166:169], v[190:193], v[106:109]
	s_waitcnt lgkmcnt(1)
	v_mfma_f32_16x16x32_bf16 v[102:105], v[158:161], v[198:201], v[102:105]
	v_mfma_f32_16x16x32_bf16 v[98:101], v[166:169], v[198:201], v[98:101]
	v_mfma_f32_16x16x32_bf16 v[126:129], v[162:165], v[178:181], v[126:129]
	v_mfma_f32_16x16x32_bf16 v[122:125], v[170:173], v[178:181], v[122:125]
	v_mfma_f32_16x16x32_bf16 v[118:121], v[162:165], v[186:189], v[118:121]
	v_mfma_f32_16x16x32_bf16 v[114:117], v[170:173], v[186:189], v[114:117]
	v_mfma_f32_16x16x32_bf16 v[110:113], v[162:165], v[194:197], v[110:113]
	v_mfma_f32_16x16x32_bf16 v[106:109], v[170:173], v[194:197], v[106:109]
	s_waitcnt lgkmcnt(0)
	v_mfma_f32_16x16x32_bf16 v[102:105], v[162:165], v[202:205], v[102:105]
	v_mfma_f32_16x16x32_bf16 v[98:101], v[170:173], v[202:205], v[98:101]
	s_setprio 0
	s_barrier
	s_add_i32 s29, s26, s27
	v_readfirstlane_b32 s43, v139
	s_add_i32 s38, s29, 0x100
	s_mov_b32 m0, s43
	ds_read_b128 v[236:239], v155
	ds_read_b128 v[240:243], v155 offset:1024
	ds_read_b128 v[244:247], v155 offset:2048
	ds_read_b128 v[248:251], v155 offset:3072
	buffer_load_dwordx4 v135, s[68:71], s38 offen lds
	s_add_i32 s38, s25, s27
	v_readfirstlane_b32 s50, v140
	s_add_i32 s43, s38, 0x100
	s_mov_b32 m0, s50
	s_add_i32 vcc_lo, vcc_lo, 2
	buffer_load_dwordx4 v135, s[68:71], s43 offen lds
	s_barrier
	s_waitcnt lgkmcnt(0)
	s_setprio 1
	s_waitcnt lgkmcnt(3)
	v_mfma_f32_16x16x32_bf16 v[94:97], v[236:239], v[174:177], v[94:97]
	s_waitcnt lgkmcnt(1)
	v_mfma_f32_16x16x32_bf16 v[90:93], v[244:247], v[174:177], v[90:93]
	v_mfma_f32_16x16x32_bf16 v[86:89], v[236:239], v[182:185], v[86:89]
	v_mfma_f32_16x16x32_bf16 v[82:85], v[244:247], v[182:185], v[82:85]
	v_mfma_f32_16x16x32_bf16 v[78:81], v[236:239], v[190:193], v[78:81]
	v_mfma_f32_16x16x32_bf16 v[74:77], v[244:247], v[190:193], v[74:77]
	v_mfma_f32_16x16x32_bf16 v[70:73], v[236:239], v[198:201], v[70:73]
	v_mfma_f32_16x16x32_bf16 v[66:69], v[244:247], v[198:201], v[66:69]
	v_mfma_f32_16x16x32_bf16 v[94:97], v[240:243], v[178:181], v[94:97]
	s_waitcnt lgkmcnt(0)
	v_mfma_f32_16x16x32_bf16 v[90:93], v[248:251], v[178:181], v[90:93]
	v_mfma_f32_16x16x32_bf16 v[86:89], v[240:243], v[186:189], v[86:89]
	v_mfma_f32_16x16x32_bf16 v[82:85], v[248:251], v[186:189], v[82:85]
	v_mfma_f32_16x16x32_bf16 v[78:81], v[240:243], v[194:197], v[78:81]
	v_mfma_f32_16x16x32_bf16 v[74:77], v[248:251], v[194:197], v[74:77]
	v_mfma_f32_16x16x32_bf16 v[70:73], v[240:243], v[202:205], v[70:73]
	v_mfma_f32_16x16x32_bf16 v[66:69], v[248:251], v[202:205], v[66:69]
	s_setprio 0
	s_add_i32 s43, s22, s27
	v_readfirstlane_b32 s51, v136
	s_add_i32 s50, s43, 0x100
	s_mov_b32 m0, s51
	s_barrier
	ds_read_b128 v[174:177], v134 offset:16384
	ds_read_b128 v[178:181], v134 offset:17408
	ds_read_b128 v[182:185], v133 offset:16384
	ds_read_b128 v[186:189], v133 offset:17408
	ds_read_b128 v[190:193], v132 offset:16384
	ds_read_b128 v[194:197], v132 offset:17408
	ds_read_b128 v[198:201], v131 offset:16384
	ds_read_b128 v[202:205], v131 offset:17408
	buffer_load_dwordx4 v135, s[4:7], s50 offen lds
	s_add_i32 s50, s21, s27
	v_readfirstlane_b32 s72, v141
	s_add_i32 s51, s50, 0x100
	s_mov_b32 m0, s72
	s_nop 0
	buffer_load_dwordx4 v135, s[4:7], s51 offen lds
	s_barrier
	s_waitcnt lgkmcnt(0)
	s_setprio 1
	s_waitcnt lgkmcnt(7)
	v_mfma_f32_16x16x32_bf16 v[62:65], v[158:161], v[174:177], v[62:65]
	v_mfma_f32_16x16x32_bf16 v[58:61], v[166:169], v[174:177], v[58:61]
	s_waitcnt lgkmcnt(5)
	v_mfma_f32_16x16x32_bf16 v[54:57], v[158:161], v[182:185], v[54:57]
	v_mfma_f32_16x16x32_bf16 v[50:53], v[166:169], v[182:185], v[50:53]
	s_waitcnt lgkmcnt(3)
	v_mfma_f32_16x16x32_bf16 v[46:49], v[158:161], v[190:193], v[46:49]
	v_mfma_f32_16x16x32_bf16 v[42:45], v[166:169], v[190:193], v[42:45]
	s_waitcnt lgkmcnt(1)
	v_mfma_f32_16x16x32_bf16 v[38:41], v[158:161], v[198:201], v[38:41]
	v_mfma_f32_16x16x32_bf16 v[34:37], v[166:169], v[198:201], v[34:37]
	v_mfma_f32_16x16x32_bf16 v[62:65], v[162:165], v[178:181], v[62:65]
	v_mfma_f32_16x16x32_bf16 v[58:61], v[170:173], v[178:181], v[58:61]
	v_mfma_f32_16x16x32_bf16 v[54:57], v[162:165], v[186:189], v[54:57]
	v_mfma_f32_16x16x32_bf16 v[50:53], v[170:173], v[186:189], v[50:53]
	v_mfma_f32_16x16x32_bf16 v[46:49], v[162:165], v[194:197], v[46:49]
	v_mfma_f32_16x16x32_bf16 v[42:45], v[170:173], v[194:197], v[42:45]
	s_waitcnt lgkmcnt(0)
	v_mfma_f32_16x16x32_bf16 v[38:41], v[162:165], v[202:205], v[38:41]
	v_mfma_f32_16x16x32_bf16 v[34:37], v[170:173], v[202:205], v[34:37]
	s_setprio 0
	s_barrier
; #define WAIT_V(n) asm volatile("s_waitcnt vmcnt(" #n ")" ::: "memory")
; #define WAIT_L(n) asm volatile("s_waitcnt lgkmcnt(" #n ")" ::: "memory")
; #define BAR __builtin_amdgcn_s_barrier()
; #define SCHED __builtin_amdgcn_sched_barrier(0)
; template <int MODE>
; __device__ __forceinline__ void gemm_tile(const int ph, const int which, const int pm, const int pn) {
;     ...
;     STAGE(SB(0, 1), RB, bcolB, t + 2);
;     WAIT_V(6); BAR; MMA(1, 1, At, B1); BAR;
;     LDB(B0, 1, 0); SCHED; LDA(At, 1, 0); STAGE(SA(0, 1), RA, brow + HALF, t + 2);
;     WAIT_L(8); BAR; WAIT_L(0); MMA(0, 0, At, B0); BAR; SCHED;
;     LDB(B1, 1, 1); STAGE(SB(1, 0), RB, bcol, t + 3);
;     BAR; WAIT_L(0); MMA(0, 1, At, B1); BAR;
;     LDA(At, 1, 1); STAGE(SA(1, 0), RA, brow, t + 3);
	s_add_i32 s51, s20, s27
	v_readfirstlane_b32 s73, v142
	s_add_i32 s72, s51, 0x100
	s_mov_b32 m0, s73
	v_readfirstlane_b32 s86, v143
	buffer_load_dwordx4 v135, s[68:71], s72 offen lds
	s_add_i32 s72, s19, s27
	s_add_i32 s73, s72, 0x100
	s_mov_b32 m0, s86
	s_nop 0
	buffer_load_dwordx4 v135, s[68:71], s73 offen lds
	s_waitcnt vmcnt(6)
	s_barrier
	s_setprio 1
	v_mfma_f32_16x16x32_bf16 v[30:33], v[236:239], v[174:177], v[30:33]
	v_mfma_f32_16x16x32_bf16 v[26:29], v[244:247], v[174:177], v[26:29]
	v_mfma_f32_16x16x32_bf16 v[22:25], v[236:239], v[182:185], v[22:25]
	v_mfma_f32_16x16x32_bf16 v[18:21], v[244:247], v[182:185], v[18:21]
	v_mfma_f32_16x16x32_bf16 v[14:17], v[236:239], v[190:193], v[14:17]
	v_mfma_f32_16x16x32_bf16 v[10:13], v[244:247], v[190:193], v[10:13]
	v_mfma_f32_16x16x32_bf16 v[6:9], v[236:239], v[198:201], v[6:9]
	v_mfma_f32_16x16x32_bf16 v[2:5], v[244:247], v[198:201], v[2:5]
	v_mfma_f32_16x16x32_bf16 v[30:33], v[240:243], v[178:181], v[30:33]
	v_mfma_f32_16x16x32_bf16 v[26:29], v[248:251], v[178:181], v[26:29]
	v_mfma_f32_16x16x32_bf16 v[22:25], v[240:243], v[186:189], v[22:25]
	v_mfma_f32_16x16x32_bf16 v[18:21], v[248:251], v[186:189], v[18:21]
	v_mfma_f32_16x16x32_bf16 v[14:17], v[240:243], v[194:197], v[14:17]
	v_mfma_f32_16x16x32_bf16 v[10:13], v[248:251], v[194:197], v[10:13]
	v_mfma_f32_16x16x32_bf16 v[6:9], v[240:243], v[202:205], v[6:9]
	v_mfma_f32_16x16x32_bf16 v[2:5], v[248:251], v[202:205], v[2:5]
	s_setprio 0
	s_barrier
	ds_read_b128 v[158:161], v144
	ds_read_b128 v[162:165], v144 offset:1024
	ds_read_b128 v[166:169], v144 offset:2048
	ds_read_b128 v[170:173], v144 offset:3072
	v_readfirstlane_b32 s73, v145
	s_addk_i32 s12, 0x100
	s_mov_b32 m0, s73
	ds_read_b128 v[174:177], v134 offset:32768
	ds_read_b128 v[178:181], v134 offset:33792
	ds_read_b128 v[182:185], v133 offset:32768
	ds_read_b128 v[186:189], v133 offset:33792
	ds_read_b128 v[190:193], v132 offset:32768
	ds_read_b128 v[194:197], v132 offset:33792
	ds_read_b128 v[198:201], v131 offset:32768
	ds_read_b128 v[202:205], v131 offset:33792
	buffer_load_dwordx4 v135, s[4:7], s12 offen lds
	v_readfirstlane_b32 s12, v146
	s_addk_i32 s13, 0x100
	s_mov_b32 m0, s12
	s_nop 0
	buffer_load_dwordx4 v135, s[4:7], s13 offen lds
	s_waitcnt lgkmcnt(8)
	s_barrier
	s_waitcnt lgkmcnt(0)
	s_setprio 1
	s_waitcnt lgkmcnt(7)
	v_mfma_f32_16x16x32_bf16 v[126:129], v[158:161], v[174:177], v[126:129]
	v_mfma_f32_16x16x32_bf16 v[122:125], v[166:169], v[174:177], v[122:125]
	s_waitcnt lgkmcnt(5)
	v_mfma_f32_16x16x32_bf16 v[118:121], v[158:161], v[182:185], v[118:121]
	v_mfma_f32_16x16x32_bf16 v[114:117], v[166:169], v[182:185], v[114:117]
	s_waitcnt lgkmcnt(3)
	v_mfma_f32_16x16x32_bf16 v[110:113], v[158:161], v[190:193], v[110:113]
	v_mfma_f32_16x16x32_bf16 v[106:109], v[166:169], v[190:193], v[106:109]
	s_waitcnt lgkmcnt(1)
	v_mfma_f32_16x16x32_bf16 v[102:105], v[158:161], v[198:201], v[102:105]
	v_mfma_f32_16x16x32_bf16 v[98:101], v[166:169], v[198:201], v[98:101]
	v_mfma_f32_16x16x32_bf16 v[126:129], v[162:165], v[178:181], v[126:129]
	v_mfma_f32_16x16x32_bf16 v[122:125], v[170:173], v[178:181], v[122:125]
	v_mfma_f32_16x16x32_bf16 v[118:121], v[162:165], v[186:189], v[118:121]
	v_mfma_f32_16x16x32_bf16 v[114:117], v[170:173], v[186:189], v[114:117]
	v_mfma_f32_16x16x32_bf16 v[110:113], v[162:165], v[194:197], v[110:113]
	v_mfma_f32_16x16x32_bf16 v[106:109], v[170:173], v[194:197], v[106:109]
	s_waitcnt lgkmcnt(0)
	v_mfma_f32_16x16x32_bf16 v[102:105], v[162:165], v[202:205], v[102:105]
	v_mfma_f32_16x16x32_bf16 v[98:101], v[170:173], v[202:205], v[98:101]
	s_setprio 0
	s_barrier
	v_readfirstlane_b32 s12, v147
	s_addk_i32 s29, 0x180
	s_mov_b32 m0, s12
	v_readfirstlane_b32 s12, v148
	ds_read_b128 v[236:239], v137
	ds_read_b128 v[240:243], v137 offset:1024
	ds_read_b128 v[244:247], v137 offset:2048
	ds_read_b128 v[248:251], v137 offset:3072
	buffer_load_dwordx4 v135, s[68:71], s29 offen lds
	s_addk_i32 s38, 0x180
	s_mov_b32 m0, s12
	s_nop 0
	buffer_load_dwordx4 v135, s[68:71], s38 offen lds
	s_barrier
	s_waitcnt lgkmcnt(0)
	s_setprio 1
	s_waitcnt lgkmcnt(3)
	v_mfma_f32_16x16x32_bf16 v[94:97], v[236:239], v[174:177], v[94:97]
	s_waitcnt lgkmcnt(1)
	v_mfma_f32_16x16x32_bf16 v[90:93], v[244:247], v[174:177], v[90:93]
	v_mfma_f32_16x16x32_bf16 v[86:89], v[236:239], v[182:185], v[86:89]
	v_mfma_f32_16x16x32_bf16 v[82:85], v[244:247], v[182:185], v[82:85]
	v_mfma_f32_16x16x32_bf16 v[78:81], v[236:239], v[190:193], v[78:81]
	v_mfma_f32_16x16x32_bf16 v[74:77], v[244:247], v[190:193], v[74:77]
	v_mfma_f32_16x16x32_bf16 v[70:73], v[236:239], v[198:201], v[70:73]
	v_mfma_f32_16x16x32_bf16 v[66:69], v[244:247], v[198:201], v[66:69]
	v_mfma_f32_16x16x32_bf16 v[94:97], v[240:243], v[178:181], v[94:97]
	s_waitcnt lgkmcnt(0)
	v_mfma_f32_16x16x32_bf16 v[90:93], v[248:251], v[178:181], v[90:93]
	v_mfma_f32_16x16x32_bf16 v[86:89], v[240:243], v[186:189], v[86:89]
	v_mfma_f32_16x16x32_bf16 v[82:85], v[248:251], v[186:189], v[82:85]
	v_mfma_f32_16x16x32_bf16 v[78:81], v[240:243], v[194:197], v[78:81]
	v_mfma_f32_16x16x32_bf16 v[74:77], v[248:251], v[194:197], v[74:77]
	v_mfma_f32_16x16x32_bf16 v[70:73], v[240:243], v[202:205], v[70:73]
	v_mfma_f32_16x16x32_bf16 v[66:69], v[248:251], v[202:205], v[66:69]
	s_setprio 0
	v_readfirstlane_b32 s12, v149
	s_addk_i32 s43, 0x180
	s_mov_b32 m0, s12
	v_readfirstlane_b32 s12, v150
	s_barrier
	ds_read_b128 v[174:177], v134 offset:49152
	ds_read_b128 v[178:181], v134 offset:50176
	ds_read_b128 v[182:185], v133 offset:49152
	ds_read_b128 v[186:189], v133 offset:50176
	ds_read_b128 v[190:193], v132 offset:49152
	ds_read_b128 v[194:197], v132 offset:50176
	ds_read_b128 v[198:201], v131 offset:49152
	ds_read_b128 v[202:205], v131 offset:50176
	buffer_load_dwordx4 v135, s[4:7], s43 offen lds
	s_addk_i32 s50, 0x180
	s_mov_b32 m0, s12
	s_nop 0
	buffer_load_dwordx4 v135, s[4:7], s50 offen lds
	s_barrier
; #define WAIT_V(n) asm volatile("s_waitcnt vmcnt(" #n ")" ::: "memory")
; #define WAIT_L(n) asm volatile("s_waitcnt lgkmcnt(" #n ")" ::: "memory")
; #define BAR __builtin_amdgcn_s_barrier()
; #define SCHED __builtin_amdgcn_sched_barrier(0)
; template <int MODE>
; __device__ __forceinline__ void gemm_tile(const int ph, const int which, const int pm, const int pn) {
;     ...
;     BAR; WAIT_L(0); MMA(1, 0, At, B0); BAR; SCHED;
;     STAGE(SB(1, 1), RB, bcolB, t + 3);
;     WAIT_V(6); BAR; MMA(1, 1, At, B1); BAR;
;   }
;   {
;     LDB(B0, 0, 0); LDA(At, 0, 0); STAGE(SA(1, 1), RA, brow + HALF, nt - 1);
;     BAR; WAIT_L(0); MMA(0, 0, At, B0); BAR;
	s_waitcnt lgkmcnt(0)
	s_setprio 1
	s_waitcnt lgkmcnt(7)
	v_mfma_f32_16x16x32_bf16 v[62:65], v[158:161], v[174:177], v[62:65]
	v_mfma_f32_16x16x32_bf16 v[58:61], v[166:169], v[174:177], v[58:61]
	s_waitcnt lgkmcnt(5)
	v_mfma_f32_16x16x32_bf16 v[54:57], v[158:161], v[182:185], v[54:57]
	v_mfma_f32_16x16x32_bf16 v[50:53], v[166:169], v[182:185], v[50:53]
	s_waitcnt lgkmcnt(3)
	v_mfma_f32_16x16x32_bf16 v[46:49], v[158:161], v[190:193], v[46:49]
	v_mfma_f32_16x16x32_bf16 v[42:45], v[166:169], v[190:193], v[42:45]
	s_waitcnt lgkmcnt(1)
	v_mfma_f32_16x16x32_bf16 v[38:41], v[158:161], v[198:201], v[38:41]
	v_mfma_f32_16x16x32_bf16 v[34:37], v[166:169], v[198:201], v[34:37]
	v_mfma_f32_16x16x32_bf16 v[62:65], v[162:165], v[178:181], v[62:65]
	v_mfma_f32_16x16x32_bf16 v[58:61], v[170:173], v[178:181], v[58:61]
	v_mfma_f32_16x16x32_bf16 v[54:57], v[162:165], v[186:189], v[54:57]
	v_mfma_f32_16x16x32_bf16 v[50:53], v[170:173], v[186:189], v[50:53]
	v_mfma_f32_16x16x32_bf16 v[46:49], v[162:165], v[194:197], v[46:49]
	v_mfma_f32_16x16x32_bf16 v[42:45], v[170:173], v[194:197], v[42:45]
	s_waitcnt lgkmcnt(0)
	v_mfma_f32_16x16x32_bf16 v[38:41], v[162:165], v[202:205], v[38:41]
	v_mfma_f32_16x16x32_bf16 v[34:37], v[170:173], v[202:205], v[34:37]
	s_setprio 0
	s_barrier
	v_readfirstlane_b32 s12, v152
	s_addk_i32 s51, 0x180
	s_mov_b32 m0, s12
	v_readfirstlane_b32 s12, v154
	buffer_load_dwordx4 v135, s[68:71], s51 offen lds
	s_addk_i32 s72, 0x180
	s_mov_b32 m0, s12
	s_nop 0
	buffer_load_dwordx4 v135, s[68:71], s72 offen lds
	s_waitcnt vmcnt(6)
	s_barrier
	s_setprio 1
	v_mfma_f32_16x16x32_bf16 v[30:33], v[236:239], v[174:177], v[30:33]
	v_mfma_f32_16x16x32_bf16 v[26:29], v[244:247], v[174:177], v[26:29]
	v_mfma_f32_16x16x32_bf16 v[22:25], v[236:239], v[182:185], v[22:25]
	v_mfma_f32_16x16x32_bf16 v[18:21], v[244:247], v[182:185], v[18:21]
	v_mfma_f32_16x16x32_bf16 v[14:17], v[236:239], v[190:193], v[14:17]
	v_mfma_f32_16x16x32_bf16 v[10:13], v[244:247], v[190:193], v[10:13]
	v_mfma_f32_16x16x32_bf16 v[6:9], v[236:239], v[198:201], v[6:9]
	v_mfma_f32_16x16x32_bf16 v[2:5], v[244:247], v[198:201], v[2:5]
	v_mfma_f32_16x16x32_bf16 v[30:33], v[240:243], v[178:181], v[30:33]
	v_mfma_f32_16x16x32_bf16 v[26:29], v[248:251], v[178:181], v[26:29]
	v_mfma_f32_16x16x32_bf16 v[22:25], v[240:243], v[186:189], v[22:25]
	v_mfma_f32_16x16x32_bf16 v[18:21], v[248:251], v[186:189], v[18:21]
	v_mfma_f32_16x16x32_bf16 v[14:17], v[240:243], v[194:197], v[14:17]
	v_mfma_f32_16x16x32_bf16 v[10:13], v[248:251], v[194:197], v[10:13]
	v_mfma_f32_16x16x32_bf16 v[6:9], v[240:243], v[202:205], v[6:9]
	v_mfma_f32_16x16x32_bf16 v[2:5], v[248:251], v[202:205], v[2:5]
	s_setprio 0
	s_addk_i32 s27, 0x100
	s_cmp_lt_u32 vcc_lo, s16
	s_cbranch_scc1 .Lgemm_head_218
	s_barrier
	s_add_i32 s6, s28, s11
	s_lshl_b32 s6, s6, 1
	v_readfirstlane_b32 s12, v153
	s_add_i32 s11, s6, 0xffffff80
	s_mov_b32 s6, s70
	s_mov_b32 s7, s71
	s_mov_b32 m0, s12
	ds_read_b128 v[140:143], v156
	ds_read_b128 v[146:149], v156 offset:1024
	ds_read_b128 v[158:161], v156 offset:2048
	ds_read_b128 v[162:165], v156 offset:3072
	ds_read_b128 v[166:169], v134
	ds_read_b128 v[170:173], v134 offset:1024
	ds_read_b128 v[174:177], v133
	ds_read_b128 v[178:181], v133 offset:1024
	ds_read_b128 v[182:185], v132
	ds_read_b128 v[186:189], v132 offset:1024
	ds_read_b128 v[190:193], v131
	ds_read_b128 v[194:197], v131 offset:1024
	buffer_load_dwordx4 v135, s[4:7], s11 offen lds
	s_add_i32 s11, s11, s10
	v_readfirstlane_b32 s10, v151
	s_mov_b32 m0, s10
	s_nop 0
	buffer_load_dwordx4 v135, s[4:7], s11 offen lds
	s_barrier
	s_waitcnt lgkmcnt(0)
	s_setprio 1
	s_waitcnt lgkmcnt(7)
	v_mfma_f32_16x16x32_bf16 v[126:129], v[140:143], v[166:169], v[126:129]
	v_mfma_f32_16x16x32_bf16 v[122:125], v[158:161], v[166:169], v[122:125]
	s_waitcnt lgkmcnt(5)
	v_mfma_f32_16x16x32_bf16 v[118:121], v[140:143], v[174:177], v[118:121]
	v_mfma_f32_16x16x32_bf16 v[114:117], v[158:161], v[174:177], v[114:117]
	s_waitcnt lgkmcnt(1)
	v_mfma_f32_16x16x32_bf16 v[102:105], v[140:143], v[190:193], v[102:105]
	v_mfma_f32_16x16x32_bf16 v[98:101], v[158:161], v[190:193], v[98:101]
	v_mfma_f32_16x16x32_bf16 v[126:129], v[146:149], v[170:173], v[126:129]
	v_mfma_f32_16x16x32_bf16 v[122:125], v[162:165], v[170:173], v[122:125]
	v_mfma_f32_16x16x32_bf16 v[118:121], v[146:149], v[178:181], v[118:121]
	v_mfma_f32_16x16x32_bf16 v[114:117], v[162:165], v[178:181], v[114:117]
	v_mfma_f32_16x16x32_bf16 v[110:113], v[140:143], v[182:185], v[110:113]
	v_mfma_f32_16x16x32_bf16 v[106:109], v[158:161], v[182:185], v[106:109]
	s_waitcnt lgkmcnt(0)
	v_mfma_f32_16x16x32_bf16 v[102:105], v[146:149], v[194:197], v[102:105]
	v_mfma_f32_16x16x32_bf16 v[98:101], v[162:165], v[194:197], v[98:101]
	v_mfma_f32_16x16x32_bf16 v[150:153], v[146:149], v[186:189], v[110:113]
	v_mfma_f32_16x16x32_bf16 v[198:201], v[162:165], v[186:189], v[106:109]
	s_setprio 0
	s_barrier
	s_nop 0
	ds_read_b128 v[106:109], v155
	ds_read_b128 v[110:113], v155 offset:1024
	ds_read_b128 v[202:205], v155 offset:2048
	ds_read_b128 v[154:157], v155 offset:3072
	s_barrier
; #define WAIT_V(n) asm volatile("s_waitcnt vmcnt(" #n ")" ::: "memory")
; #define WAIT_L(n) asm volatile("s_waitcnt lgkmcnt(" #n ")" ::: "memory")
; #define BAR __builtin_amdgcn_s_barrier()
; template <int MODE>
; __device__ __forceinline__ void gemm_tile(const int ph, const int which, const int pm, const int pn) {
;     ...
;     LDB(B1, 0, 1); BAR; WAIT_L(0); MMA(0, 1, At, B1); BAR;
;     LDA(At, 0, 1); WAIT_V(4); BAR; WAIT_L(0); MMA(1, 0, At, B0); MMA(1, 1, At, B1); BAR;
;   }
;   {
;     LDB(B0, 1, 0); LDA(At, 1, 0); WAIT_V(2); BAR; WAIT_L(0); MMA(0, 0, At, B0); BAR;
	s_waitcnt lgkmcnt(0)
	s_setprio 1
	s_waitcnt lgkmcnt(3)
	v_mfma_f32_16x16x32_bf16 v[86:89], v[106:109], v[174:177], v[86:89]
	s_waitcnt lgkmcnt(1)
	v_mfma_f32_16x16x32_bf16 v[82:85], v[202:205], v[174:177], v[82:85]
	v_mfma_f32_16x16x32_bf16 v[70:73], v[106:109], v[190:193], v[70:73]
	v_mfma_f32_16x16x32_bf16 v[66:69], v[202:205], v[190:193], v[66:69]
	v_mfma_f32_16x16x32_bf16 v[94:97], v[106:109], v[166:169], v[94:97]
	v_mfma_f32_16x16x32_bf16 v[90:93], v[202:205], v[166:169], v[90:93]
	v_mfma_f32_16x16x32_bf16 v[86:89], v[110:113], v[178:181], v[86:89]
	s_waitcnt lgkmcnt(0)
	v_mfma_f32_16x16x32_bf16 v[82:85], v[154:157], v[178:181], v[82:85]
	v_mfma_f32_16x16x32_bf16 v[78:81], v[106:109], v[182:185], v[78:81]
	v_mfma_f32_16x16x32_bf16 v[74:77], v[202:205], v[182:185], v[74:77]
	v_mfma_f32_16x16x32_bf16 v[70:73], v[110:113], v[194:197], v[70:73]
	v_mfma_f32_16x16x32_bf16 v[66:69], v[154:157], v[194:197], v[66:69]
	v_mfma_f32_16x16x32_bf16 v[236:239], v[110:113], v[170:173], v[94:97]
	v_mfma_f32_16x16x32_bf16 v[166:169], v[154:157], v[170:173], v[90:93]
	v_mfma_f32_16x16x32_bf16 v[170:173], v[110:113], v[186:189], v[78:81]
	v_mfma_f32_16x16x32_bf16 v[174:177], v[154:157], v[186:189], v[74:77]
	s_setprio 0
	s_barrier
	s_nop 0
	ds_read_b128 v[74:77], v134 offset:16384
	ds_read_b128 v[78:81], v134 offset:17408
	ds_read_b128 v[90:93], v133 offset:16384
	ds_read_b128 v[94:97], v133 offset:17408
	ds_read_b128 v[178:181], v132 offset:16384
	ds_read_b128 v[182:185], v132 offset:17408
	ds_read_b128 v[186:189], v131 offset:16384
	ds_read_b128 v[190:193], v131 offset:17408
	s_waitcnt vmcnt(4)
	s_barrier
	s_waitcnt lgkmcnt(0)
	s_setprio 1
	s_waitcnt lgkmcnt(7)
	v_mfma_f32_16x16x32_bf16 v[62:65], v[140:143], v[74:77], v[62:65]
	v_mfma_f32_16x16x32_bf16 v[58:61], v[158:161], v[74:77], v[58:61]
	s_waitcnt lgkmcnt(5)
	v_mfma_f32_16x16x32_bf16 v[54:57], v[140:143], v[90:93], v[54:57]
	v_mfma_f32_16x16x32_bf16 v[50:53], v[158:161], v[90:93], v[50:53]
	s_waitcnt lgkmcnt(1)
	v_mfma_f32_16x16x32_bf16 v[38:41], v[140:143], v[186:189], v[38:41]
	v_mfma_f32_16x16x32_bf16 v[34:37], v[158:161], v[186:189], v[34:37]
	v_mfma_f32_16x16x32_bf16 v[62:65], v[146:149], v[78:81], v[62:65]
	v_mfma_f32_16x16x32_bf16 v[58:61], v[162:165], v[78:81], v[58:61]
	v_mfma_f32_16x16x32_bf16 v[54:57], v[146:149], v[94:97], v[54:57]
	v_mfma_f32_16x16x32_bf16 v[50:53], v[162:165], v[94:97], v[50:53]
	v_mfma_f32_16x16x32_bf16 v[46:49], v[140:143], v[178:181], v[46:49]
	v_mfma_f32_16x16x32_bf16 v[42:45], v[158:161], v[178:181], v[42:45]
	s_waitcnt lgkmcnt(0)
	v_mfma_f32_16x16x32_bf16 v[38:41], v[146:149], v[190:193], v[38:41]
	v_mfma_f32_16x16x32_bf16 v[34:37], v[162:165], v[190:193], v[34:37]
	v_mfma_f32_16x16x32_bf16 v[194:197], v[146:149], v[182:185], v[46:49]
	v_mfma_f32_16x16x32_bf16 v[240:243], v[162:165], v[182:185], v[42:45]
	v_mfma_f32_16x16x32_bf16 v[22:25], v[106:109], v[90:93], v[22:25]
	v_mfma_f32_16x16x32_bf16 v[18:21], v[202:205], v[90:93], v[18:21]
	v_mfma_f32_16x16x32_bf16 v[6:9], v[106:109], v[186:189], v[6:9]
	v_mfma_f32_16x16x32_bf16 v[2:5], v[202:205], v[186:189], v[2:5]
	v_mfma_f32_16x16x32_bf16 v[30:33], v[106:109], v[74:77], v[30:33]
	v_mfma_f32_16x16x32_bf16 v[26:29], v[202:205], v[74:77], v[26:29]
	v_mfma_f32_16x16x32_bf16 v[22:25], v[110:113], v[94:97], v[22:25]
	v_mfma_f32_16x16x32_bf16 v[18:21], v[154:157], v[94:97], v[18:21]
	v_mfma_f32_16x16x32_bf16 v[14:17], v[106:109], v[178:181], v[14:17]
	v_mfma_f32_16x16x32_bf16 v[10:13], v[202:205], v[178:181], v[10:13]
	v_mfma_f32_16x16x32_bf16 v[6:9], v[110:113], v[190:193], v[6:9]
	v_mfma_f32_16x16x32_bf16 v[2:5], v[154:157], v[190:193], v[2:5]
	v_mfma_f32_16x16x32_bf16 v[140:143], v[110:113], v[78:81], v[30:33]
	v_mfma_f32_16x16x32_bf16 v[146:149], v[154:157], v[78:81], v[26:29]
	v_mfma_f32_16x16x32_bf16 v[158:161], v[110:113], v[182:185], v[14:17]
	v_mfma_f32_16x16x32_bf16 v[162:165], v[154:157], v[182:185], v[10:13]
	s_setprio 0
	s_barrier
	s_nop 0
	ds_read_b128 v[10:13], v144
	ds_read_b128 v[14:17], v144 offset:1024
	ds_read_b128 v[154:157], v144 offset:2048
	ds_read_b128 v[178:181], v144 offset:3072
	ds_read_b128 v[26:29], v134 offset:32768
	ds_read_b128 v[30:33], v134 offset:33792
	ds_read_b128 v[42:45], v133 offset:32768
	ds_read_b128 v[46:49], v133 offset:33792
	ds_read_b128 v[182:185], v132 offset:32768
	ds_read_b128 v[186:189], v132 offset:33792
	ds_read_b128 v[190:193], v131 offset:32768
	ds_read_b128 v[202:205], v131 offset:33792
	s_waitcnt vmcnt(2)
	s_barrier
; #define WAIT_V(n) asm volatile("s_waitcnt vmcnt(" #n ")" ::: "memory")
; #define WAIT_L(n) asm volatile("s_waitcnt lgkmcnt(" #n ")" ::: "memory")
; #define BAR __builtin_amdgcn_s_barrier()
; template <int MODE>
; __device__ __forceinline__ void gemm_tile(const int ph, const int which, const int pm, const int pn) {
;     ...
;     LDB(B0, 1, 0); LDA(At, 1, 0); WAIT_V(2); BAR; WAIT_L(0); MMA(0, 0, At, B0); BAR;
;     LDB(B1, 1, 1); WAIT_V(0); BAR; WAIT_L(0); MMA(0, 1, At, B1); BAR;
;     LDA(At, 1, 1); BAR; WAIT_L(0); MMA(1, 0, At, B0); MMA(1, 1, At, B1); BAR;
;   }
;   if (wr == 0) BAR;
	s_waitcnt lgkmcnt(0)
	s_setprio 1
	s_waitcnt lgkmcnt(7)
	v_mfma_f32_16x16x32_bf16 v[74:77], v[10:13], v[26:29], v[126:129]
	s_waitcnt lgkmcnt(6)
	v_mfma_f32_16x16x32_bf16 v[126:129], v[14:17], v[30:33], v[74:77]
	v_mfma_f32_16x16x32_bf16 v[74:77], v[154:157], v[26:29], v[122:125]
	v_mfma_f32_16x16x32_bf16 v[122:125], v[178:181], v[30:33], v[74:77]
	s_waitcnt lgkmcnt(5)
	v_mfma_f32_16x16x32_bf16 v[74:77], v[10:13], v[42:45], v[118:121]
	s_waitcnt lgkmcnt(4)
	v_mfma_f32_16x16x32_bf16 v[110:113], v[14:17], v[46:49], v[74:77]
	v_mfma_f32_16x16x32_bf16 v[74:77], v[154:157], v[42:45], v[114:117]
	v_mfma_f32_16x16x32_bf16 v[106:109], v[178:181], v[46:49], v[74:77]
	s_waitcnt lgkmcnt(3)
	v_mfma_f32_16x16x32_bf16 v[74:77], v[10:13], v[182:185], v[150:153]
	s_waitcnt lgkmcnt(2)
	v_mfma_f32_16x16x32_bf16 v[94:97], v[14:17], v[186:189], v[74:77]
	v_mfma_f32_16x16x32_bf16 v[74:77], v[154:157], v[182:185], v[198:201]
	v_mfma_f32_16x16x32_bf16 v[90:93], v[178:181], v[186:189], v[74:77]
	s_waitcnt lgkmcnt(1)
	v_mfma_f32_16x16x32_bf16 v[74:77], v[10:13], v[190:193], v[102:105]
	s_waitcnt lgkmcnt(0)
	v_mfma_f32_16x16x32_bf16 v[78:81], v[14:17], v[202:205], v[74:77]
	v_mfma_f32_16x16x32_bf16 v[74:77], v[154:157], v[190:193], v[98:101]
	v_mfma_f32_16x16x32_bf16 v[74:77], v[178:181], v[202:205], v[74:77]
	s_setprio 0
	s_barrier
	ds_read_b128 v[150:153], v137
	ds_read_b128 v[198:201], v137 offset:1024
	ds_read_b128 v[244:247], v137 offset:2048
	ds_read_b128 v[248:251], v137 offset:3072
	s_waitcnt vmcnt(0)
	s_barrier
	s_waitcnt lgkmcnt(0)
	s_setprio 1
	s_waitcnt lgkmcnt(3)
	v_mfma_f32_16x16x32_bf16 v[98:101], v[150:153], v[26:29], v[236:239]
	s_waitcnt lgkmcnt(1)
	v_mfma_f32_16x16x32_bf16 v[26:29], v[244:247], v[26:29], v[166:169]
	s_waitcnt lgkmcnt(0)
	v_mfma_f32_16x16x32_bf16 v[114:117], v[248:251], v[30:33], v[26:29]
	v_mfma_f32_16x16x32_bf16 v[26:29], v[150:153], v[42:45], v[86:89]
	v_mfma_f32_16x16x32_bf16 v[102:105], v[198:201], v[46:49], v[26:29]
	v_mfma_f32_16x16x32_bf16 v[26:29], v[244:247], v[42:45], v[82:85]
	v_mfma_f32_16x16x32_bf16 v[118:121], v[198:201], v[30:33], v[98:101]
	v_mfma_f32_16x16x32_bf16 v[98:101], v[248:251], v[46:49], v[26:29]
	v_mfma_f32_16x16x32_bf16 v[26:29], v[150:153], v[182:185], v[170:173]
	v_mfma_f32_16x16x32_bf16 v[86:89], v[198:201], v[186:189], v[26:29]
	v_mfma_f32_16x16x32_bf16 v[26:29], v[244:247], v[182:185], v[174:177]
	v_mfma_f32_16x16x32_bf16 v[82:85], v[248:251], v[186:189], v[26:29]
	v_mfma_f32_16x16x32_bf16 v[26:29], v[150:153], v[190:193], v[70:73]
	v_mfma_f32_16x16x32_bf16 v[70:73], v[198:201], v[202:205], v[26:29]
	v_mfma_f32_16x16x32_bf16 v[26:29], v[244:247], v[190:193], v[66:69]
	v_mfma_f32_16x16x32_bf16 v[66:69], v[248:251], v[202:205], v[26:29]
	s_setprio 0
	s_barrier
	ds_read_b128 v[166:169], v134 offset:49152
	ds_read_b128 v[134:137], v134 offset:50176
	ds_read_b128 v[170:173], v133 offset:49152
	ds_read_b128 v[174:177], v133 offset:50176
	ds_read_b128 v[182:185], v132 offset:49152
	ds_read_b128 v[186:189], v132 offset:50176
	ds_read_b128 v[190:193], v131 offset:49152
	ds_read_b128 v[202:205], v131 offset:50176
	s_barrier
	s_waitcnt lgkmcnt(0)
	s_setprio 1
	s_waitcnt lgkmcnt(7)
	v_mfma_f32_16x16x32_bf16 v[26:29], v[10:13], v[166:169], v[62:65]
	s_waitcnt lgkmcnt(6)
	v_mfma_f32_16x16x32_bf16 v[62:65], v[14:17], v[134:137], v[26:29]
	v_mfma_f32_16x16x32_bf16 v[26:29], v[154:157], v[166:169], v[58:61]
	v_mfma_f32_16x16x32_bf16 v[58:61], v[178:181], v[134:137], v[26:29]
	s_waitcnt lgkmcnt(5)
	v_mfma_f32_16x16x32_bf16 v[26:29], v[10:13], v[170:173], v[54:57]
	s_waitcnt lgkmcnt(4)
	v_mfma_f32_16x16x32_bf16 v[46:49], v[14:17], v[174:177], v[26:29]
	v_mfma_f32_16x16x32_bf16 v[26:29], v[154:157], v[170:173], v[50:53]
	v_mfma_f32_16x16x32_bf16 v[42:45], v[178:181], v[174:177], v[26:29]
	s_waitcnt lgkmcnt(3)
	v_mfma_f32_16x16x32_bf16 v[26:29], v[10:13], v[182:185], v[194:197]
	s_waitcnt lgkmcnt(1)
	v_mfma_f32_16x16x32_bf16 v[10:13], v[10:13], v[190:193], v[38:41]
	v_mfma_f32_16x16x32_bf16 v[30:33], v[14:17], v[186:189], v[26:29]
	v_mfma_f32_16x16x32_bf16 v[26:29], v[154:157], v[182:185], v[240:243]
	s_waitcnt lgkmcnt(0)
	v_mfma_f32_16x16x32_bf16 v[14:17], v[14:17], v[202:205], v[10:13]
	v_mfma_f32_16x16x32_bf16 v[10:13], v[154:157], v[190:193], v[34:37]
	v_mfma_f32_16x16x32_bf16 v[26:29], v[178:181], v[186:189], v[26:29]
	v_mfma_f32_16x16x32_bf16 v[10:13], v[178:181], v[202:205], v[10:13]
	v_mfma_f32_16x16x32_bf16 v[34:37], v[150:153], v[166:169], v[140:143]
	v_mfma_f32_16x16x32_bf16 v[54:57], v[198:201], v[134:137], v[34:37]
	v_mfma_f32_16x16x32_bf16 v[34:37], v[244:247], v[166:169], v[146:149]
	v_mfma_f32_16x16x32_bf16 v[18:21], v[244:247], v[170:173], v[18:21]
	v_mfma_f32_16x16x32_bf16 v[50:53], v[248:251], v[134:137], v[34:37]
	v_mfma_f32_16x16x32_bf16 v[22:25], v[150:153], v[170:173], v[22:25]
	v_mfma_f32_16x16x32_bf16 v[34:37], v[248:251], v[174:177], v[18:21]
	v_mfma_f32_16x16x32_bf16 v[18:21], v[150:153], v[182:185], v[158:161]
	v_mfma_f32_16x16x32_bf16 v[38:41], v[198:201], v[174:177], v[22:25]
	v_mfma_f32_16x16x32_bf16 v[22:25], v[198:201], v[186:189], v[18:21]
	v_mfma_f32_16x16x32_bf16 v[18:21], v[244:247], v[182:185], v[162:165]
	v_mfma_f32_16x16x32_bf16 v[6:9], v[150:153], v[190:193], v[6:9]
	v_mfma_f32_16x16x32_bf16 v[2:5], v[244:247], v[190:193], v[2:5]
	v_mfma_f32_16x16x32_bf16 v[18:21], v[248:251], v[186:189], v[18:21]
	v_mfma_f32_16x16x32_bf16 v[6:9], v[198:201], v[202:205], v[6:9]
	v_mfma_f32_16x16x32_bf16 v[2:5], v[248:251], v[202:205], v[2:5]
	s_setprio 0
	s_movk_i32 s4, 0x100
	v_cmp_gt_u32_e32 vcc, s4, v0
	s_barrier
	s_and_saveexec_b64 s[4:5], vcc
	s_cbranch_execz .LBB0_221
	s_barrier

; #define WAIT_L(n) asm volatile("s_waitcnt lgkmcnt(" #n ")" ::: "memory")
; #define BAR __builtin_amdgcn_s_barrier()
; #define SCHED __builtin_amdgcn_sched_barrier(0)
; template <int MODE>
; __device__ __forceinline__ void gemm_tile(const int ph, const int which, const int pm, const int pn) {
;     ...
;     LDB(B0, 0, 0); SCHED; LDA(At, 0, 0); STAGE(SA(1, 1), RA, brow + HALF, t + 1);
;     WAIT_L(8); BAR; WAIT_L(0); MMA(0, 0, At, B0); BAR; SCHED;
;     LDB(B1, 0, 1); STAGE(SB(0, 0), RB, bcol, t + 2);
;     BAR; WAIT_L(0); MMA(0, 1, At, B1); BAR;
;     LDA(At, 0, 1); STAGE(SA(0, 0), RA, brow, t + 2);
;     BAR; WAIT_L(0); MMA(1, 0, At, B0); BAR; SCHED;
.LBB0_370:
	ds_read_b128 v[156:159], v154
	ds_read_b128 v[168:171], v154 offset:1024
	ds_read_b128 v[172:175], v154 offset:2048
	ds_read_b128 v[176:179], v154 offset:3072
	s_add_i32 s12, s10, s21
	v_readfirstlane_b32 s23, v151
	s_add_i32 s13, s12, 0x80
	s_mov_b32 m0, s23
	ds_read_b128 v[180:183], v141
	ds_read_b128 v[184:187], v141 offset:1024
	ds_read_b128 v[188:191], v140
	ds_read_b128 v[192:195], v140 offset:1024
	ds_read_b128 v[196:199], v139
	ds_read_b128 v[200:203], v139 offset:1024
	ds_read_b128 v[204:207], v138
	ds_read_b128 v[236:239], v138 offset:1024
	buffer_load_dwordx4 v130, s[4:7], s13 offen lds
	s_add_i32 s13, s3, s21
	v_readfirstlane_b32 s27, v149
	s_add_i32 s23, s13, 0x80
	s_mov_b32 m0, s27
	s_nop 0
	buffer_load_dwordx4 v130, s[4:7], s23 offen lds
	s_waitcnt lgkmcnt(8)
	s_barrier
	s_waitcnt lgkmcnt(0)
	s_setprio 1
	s_waitcnt lgkmcnt(7)
	v_mfma_f32_16x16x32_bf16 v[2:5], v[156:159], v[180:183], v[2:5]
	v_mfma_f32_16x16x32_bf16 v[6:9], v[172:175], v[180:183], v[6:9]
	s_waitcnt lgkmcnt(5)
	v_mfma_f32_16x16x32_bf16 v[18:21], v[156:159], v[188:191], v[18:21]
	v_mfma_f32_16x16x32_bf16 v[30:33], v[172:175], v[188:191], v[30:33]
	s_waitcnt lgkmcnt(3)
	v_mfma_f32_16x16x32_bf16 v[42:45], v[156:159], v[196:199], v[42:45]
	v_mfma_f32_16x16x32_bf16 v[54:57], v[172:175], v[196:199], v[54:57]
	s_waitcnt lgkmcnt(1)
	v_mfma_f32_16x16x32_bf16 v[66:69], v[156:159], v[204:207], v[66:69]
	v_mfma_f32_16x16x32_bf16 v[78:81], v[172:175], v[204:207], v[78:81]
	v_mfma_f32_16x16x32_bf16 v[2:5], v[168:171], v[184:187], v[2:5]
	v_mfma_f32_16x16x32_bf16 v[6:9], v[176:179], v[184:187], v[6:9]
	v_mfma_f32_16x16x32_bf16 v[18:21], v[168:171], v[192:195], v[18:21]
	v_mfma_f32_16x16x32_bf16 v[30:33], v[176:179], v[192:195], v[30:33]
	v_mfma_f32_16x16x32_bf16 v[42:45], v[168:171], v[200:203], v[42:45]
	v_mfma_f32_16x16x32_bf16 v[54:57], v[176:179], v[200:203], v[54:57]
	s_waitcnt lgkmcnt(0)
	v_mfma_f32_16x16x32_bf16 v[66:69], v[168:171], v[236:239], v[66:69]
	v_mfma_f32_16x16x32_bf16 v[78:81], v[176:179], v[236:239], v[78:81]
	s_setprio 0
	s_barrier
	s_add_i32 s23, s20, s21
	v_readfirstlane_b32 s28, v132
	s_add_i32 s27, s23, 0x100
	s_mov_b32 m0, s28
	ds_read_b128 v[240:243], v153
	ds_read_b128 v[244:247], v153 offset:1024
	ds_read_b128 v[248:251], v153 offset:2048
	ds_read_b128 v[210:213], v153 offset:3072
	buffer_load_dwordx4 v130, s[68:71], s27 offen lds
	s_add_i32 s27, s19, s21
	v_readfirstlane_b32 s29, v133
	s_add_i32 s28, s27, 0x100
	s_mov_b32 m0, s29
	s_add_i32 s22, s22, 2
	buffer_load_dwordx4 v130, s[68:71], s28 offen lds
	s_barrier
	s_waitcnt lgkmcnt(0)
	s_setprio 1
	s_waitcnt lgkmcnt(3)
	v_mfma_f32_16x16x32_bf16 v[10:13], v[240:243], v[180:183], v[10:13]
	s_waitcnt lgkmcnt(1)
	v_mfma_f32_16x16x32_bf16 v[22:25], v[248:251], v[180:183], v[22:25]
	v_mfma_f32_16x16x32_bf16 v[34:37], v[240:243], v[188:191], v[34:37]
	v_mfma_f32_16x16x32_bf16 v[46:49], v[248:251], v[188:191], v[46:49]
	v_mfma_f32_16x16x32_bf16 v[58:61], v[240:243], v[196:199], v[58:61]
	v_mfma_f32_16x16x32_bf16 v[70:73], v[248:251], v[196:199], v[70:73]
	v_mfma_f32_16x16x32_bf16 v[82:85], v[240:243], v[204:207], v[82:85]
	v_mfma_f32_16x16x32_bf16 v[94:97], v[248:251], v[204:207], v[94:97]
	v_mfma_f32_16x16x32_bf16 v[10:13], v[244:247], v[184:187], v[10:13]
	s_waitcnt lgkmcnt(0)
	v_mfma_f32_16x16x32_bf16 v[22:25], v[210:213], v[184:187], v[22:25]
	v_mfma_f32_16x16x32_bf16 v[34:37], v[244:247], v[192:195], v[34:37]
	v_mfma_f32_16x16x32_bf16 v[46:49], v[210:213], v[192:195], v[46:49]
	v_mfma_f32_16x16x32_bf16 v[58:61], v[244:247], v[200:203], v[58:61]
	v_mfma_f32_16x16x32_bf16 v[70:73], v[210:213], v[200:203], v[70:73]
	v_mfma_f32_16x16x32_bf16 v[82:85], v[244:247], v[236:239], v[82:85]
	v_mfma_f32_16x16x32_bf16 v[94:97], v[210:213], v[236:239], v[94:97]
	s_setprio 0
	s_add_i32 s28, s18, s21
	v_readfirstlane_b32 s38, v131
	s_add_i32 s29, s28, 0x100
	s_mov_b32 m0, s38
	s_barrier
	ds_read_b128 v[180:183], v141 offset:16384
	ds_read_b128 v[184:187], v141 offset:17408
	ds_read_b128 v[188:191], v140 offset:16384
	ds_read_b128 v[192:195], v140 offset:17408
	ds_read_b128 v[196:199], v139 offset:16384
	ds_read_b128 v[200:203], v139 offset:17408
	ds_read_b128 v[204:207], v138 offset:16384
	ds_read_b128 v[236:239], v138 offset:17408
	buffer_load_dwordx4 v130, s[4:7], s29 offen lds
	s_add_i32 s29, s17, s21
	v_readfirstlane_b32 s43, v134
	s_add_i32 s38, s29, 0x100
	s_mov_b32 m0, s43
	s_nop 0
	buffer_load_dwordx4 v130, s[4:7], s38 offen lds
	s_barrier
	s_waitcnt lgkmcnt(0)
	s_setprio 1
	s_waitcnt lgkmcnt(7)
	v_mfma_f32_16x16x32_bf16 v[14:17], v[156:159], v[180:183], v[14:17]
	v_mfma_f32_16x16x32_bf16 v[26:29], v[172:175], v[180:183], v[26:29]
	s_waitcnt lgkmcnt(5)
	v_mfma_f32_16x16x32_bf16 v[38:41], v[156:159], v[188:191], v[38:41]
	v_mfma_f32_16x16x32_bf16 v[50:53], v[172:175], v[188:191], v[50:53]
	s_waitcnt lgkmcnt(3)
	v_mfma_f32_16x16x32_bf16 v[62:65], v[156:159], v[196:199], v[62:65]
	v_mfma_f32_16x16x32_bf16 v[74:77], v[172:175], v[196:199], v[74:77]
	s_waitcnt lgkmcnt(1)
	v_mfma_f32_16x16x32_bf16 v[86:89], v[156:159], v[204:207], v[86:89]
	v_mfma_f32_16x16x32_bf16 v[98:101], v[172:175], v[204:207], v[98:101]
	v_mfma_f32_16x16x32_bf16 v[14:17], v[168:171], v[184:187], v[14:17]
	v_mfma_f32_16x16x32_bf16 v[26:29], v[176:179], v[184:187], v[26:29]
	v_mfma_f32_16x16x32_bf16 v[38:41], v[168:171], v[192:195], v[38:41]
	v_mfma_f32_16x16x32_bf16 v[50:53], v[176:179], v[192:195], v[50:53]
	v_mfma_f32_16x16x32_bf16 v[62:65], v[168:171], v[200:203], v[62:65]
	v_mfma_f32_16x16x32_bf16 v[74:77], v[176:179], v[200:203], v[74:77]
	s_waitcnt lgkmcnt(0)
	v_mfma_f32_16x16x32_bf16 v[86:89], v[168:171], v[236:239], v[86:89]
	v_mfma_f32_16x16x32_bf16 v[98:101], v[176:179], v[236:239], v[98:101]
	s_setprio 0
	s_barrier
; #define WAIT_V(n) asm volatile("s_waitcnt vmcnt(" #n ")" ::: "memory")
; #define WAIT_L(n) asm volatile("s_waitcnt lgkmcnt(" #n ")" ::: "memory")
; #define BAR __builtin_amdgcn_s_barrier()
; #define SCHED __builtin_amdgcn_sched_barrier(0)
; template <int MODE>
; __device__ __forceinline__ void gemm_tile(const int ph, const int which, const int pm, const int pn) {
;     ...
;     STAGE(SB(0, 1), RB, bcolB, t + 2);
;     WAIT_V(6); BAR; MMA(1, 1, At, B1); BAR;
;     LDB(B0, 1, 0); SCHED; LDA(At, 1, 0); STAGE(SA(0, 1), RA, brow + HALF, t + 2);
;     WAIT_L(8); BAR; WAIT_L(0); MMA(0, 0, At, B0); BAR; SCHED;
;     LDB(B1, 1, 1); STAGE(SB(1, 0), RB, bcol, t + 3);
;     BAR; WAIT_L(0); MMA(0, 1, At, B1); BAR;
;     LDA(At, 1, 1); STAGE(SA(1, 0), RA, brow, t + 3);
	s_add_i32 s38, s16, s21
	v_readfirstlane_b32 s50, v135
	s_add_i32 s43, s38, 0x100
	s_mov_b32 m0, s50
	v_readfirstlane_b32 s51, v136
	buffer_load_dwordx4 v130, s[68:71], s43 offen lds
	s_add_i32 s43, s11, s21
	s_add_i32 s50, s43, 0x100
	s_mov_b32 m0, s51
	s_nop 0
	buffer_load_dwordx4 v130, s[68:71], s50 offen lds
	s_waitcnt vmcnt(6)
	s_barrier
	s_setprio 1
	v_mfma_f32_16x16x32_bf16 v[90:93], v[240:243], v[180:183], v[90:93]
	v_mfma_f32_16x16x32_bf16 v[102:105], v[248:251], v[180:183], v[102:105]
	v_mfma_f32_16x16x32_bf16 v[106:109], v[240:243], v[188:191], v[106:109]
	v_mfma_f32_16x16x32_bf16 v[110:113], v[248:251], v[188:191], v[110:113]
	v_mfma_f32_16x16x32_bf16 v[114:117], v[240:243], v[196:199], v[114:117]
	v_mfma_f32_16x16x32_bf16 v[118:121], v[248:251], v[196:199], v[118:121]
	v_mfma_f32_16x16x32_bf16 v[122:125], v[240:243], v[204:207], v[122:125]
	v_mfma_f32_16x16x32_bf16 v[126:129], v[248:251], v[204:207], v[126:129]
	v_mfma_f32_16x16x32_bf16 v[90:93], v[244:247], v[184:187], v[90:93]
	v_mfma_f32_16x16x32_bf16 v[102:105], v[210:213], v[184:187], v[102:105]
	v_mfma_f32_16x16x32_bf16 v[106:109], v[244:247], v[192:195], v[106:109]
	v_mfma_f32_16x16x32_bf16 v[110:113], v[210:213], v[192:195], v[110:113]
	v_mfma_f32_16x16x32_bf16 v[114:117], v[244:247], v[200:203], v[114:117]
	v_mfma_f32_16x16x32_bf16 v[118:121], v[210:213], v[200:203], v[118:121]
	v_mfma_f32_16x16x32_bf16 v[122:125], v[244:247], v[236:239], v[122:125]
	v_mfma_f32_16x16x32_bf16 v[126:129], v[210:213], v[236:239], v[126:129]
	s_setprio 0
	s_barrier
	ds_read_b128 v[156:159], v137
	ds_read_b128 v[168:171], v137 offset:1024
	ds_read_b128 v[172:175], v137 offset:2048
	ds_read_b128 v[176:179], v137 offset:3072
	v_readfirstlane_b32 s50, v143
	s_addk_i32 s12, 0x100
	s_mov_b32 m0, s50
	ds_read_b128 v[180:183], v141 offset:32768
	ds_read_b128 v[184:187], v141 offset:33792
	ds_read_b128 v[188:191], v140 offset:32768
	ds_read_b128 v[192:195], v140 offset:33792
	ds_read_b128 v[196:199], v139 offset:32768
	ds_read_b128 v[200:203], v139 offset:33792
	ds_read_b128 v[204:207], v138 offset:32768
	ds_read_b128 v[210:213], v138 offset:33792
	buffer_load_dwordx4 v130, s[4:7], s12 offen lds
	v_readfirstlane_b32 s12, v144
	s_addk_i32 s13, 0x100
	s_mov_b32 m0, s12
	s_nop 0
	buffer_load_dwordx4 v130, s[4:7], s13 offen lds
	s_waitcnt lgkmcnt(8)
	s_barrier
	s_waitcnt lgkmcnt(0)
	s_setprio 1
	s_waitcnt lgkmcnt(7)
	v_mfma_f32_16x16x32_bf16 v[2:5], v[156:159], v[180:183], v[2:5]
	v_mfma_f32_16x16x32_bf16 v[6:9], v[172:175], v[180:183], v[6:9]
	s_waitcnt lgkmcnt(5)
	v_mfma_f32_16x16x32_bf16 v[18:21], v[156:159], v[188:191], v[18:21]
	v_mfma_f32_16x16x32_bf16 v[30:33], v[172:175], v[188:191], v[30:33]
	s_waitcnt lgkmcnt(3)
	v_mfma_f32_16x16x32_bf16 v[42:45], v[156:159], v[196:199], v[42:45]
	v_mfma_f32_16x16x32_bf16 v[54:57], v[172:175], v[196:199], v[54:57]
	s_waitcnt lgkmcnt(1)
	v_mfma_f32_16x16x32_bf16 v[66:69], v[156:159], v[204:207], v[66:69]
	v_mfma_f32_16x16x32_bf16 v[78:81], v[172:175], v[204:207], v[78:81]
	v_mfma_f32_16x16x32_bf16 v[2:5], v[168:171], v[184:187], v[2:5]
	v_mfma_f32_16x16x32_bf16 v[6:9], v[176:179], v[184:187], v[6:9]
	v_mfma_f32_16x16x32_bf16 v[18:21], v[168:171], v[192:195], v[18:21]
	v_mfma_f32_16x16x32_bf16 v[30:33], v[176:179], v[192:195], v[30:33]
	v_mfma_f32_16x16x32_bf16 v[42:45], v[168:171], v[200:203], v[42:45]
	v_mfma_f32_16x16x32_bf16 v[54:57], v[176:179], v[200:203], v[54:57]
	s_waitcnt lgkmcnt(0)
	v_mfma_f32_16x16x32_bf16 v[66:69], v[168:171], v[210:213], v[66:69]
	v_mfma_f32_16x16x32_bf16 v[78:81], v[176:179], v[210:213], v[78:81]
	s_setprio 0
	s_barrier
	v_readfirstlane_b32 s12, v145
	s_addk_i32 s23, 0x180
	s_mov_b32 m0, s12
	v_readfirstlane_b32 s12, v146
	ds_read_b128 v[236:239], v142
	ds_read_b128 v[240:243], v142 offset:1024
	ds_read_b128 v[244:247], v142 offset:2048
	ds_read_b128 v[248:251], v142 offset:3072
	buffer_load_dwordx4 v130, s[68:71], s23 offen lds
	s_addk_i32 s27, 0x180
	s_mov_b32 m0, s12
	s_nop 0
	buffer_load_dwordx4 v130, s[68:71], s27 offen lds
	s_barrier
	s_waitcnt lgkmcnt(0)
	s_setprio 1
	s_waitcnt lgkmcnt(3)
	v_mfma_f32_16x16x32_bf16 v[10:13], v[236:239], v[180:183], v[10:13]
	s_waitcnt lgkmcnt(1)
	v_mfma_f32_16x16x32_bf16 v[22:25], v[244:247], v[180:183], v[22:25]
	v_mfma_f32_16x16x32_bf16 v[34:37], v[236:239], v[188:191], v[34:37]
	v_mfma_f32_16x16x32_bf16 v[46:49], v[244:247], v[188:191], v[46:49]
	v_mfma_f32_16x16x32_bf16 v[58:61], v[236:239], v[196:199], v[58:61]
	v_mfma_f32_16x16x32_bf16 v[70:73], v[244:247], v[196:199], v[70:73]
	v_mfma_f32_16x16x32_bf16 v[82:85], v[236:239], v[204:207], v[82:85]
	v_mfma_f32_16x16x32_bf16 v[94:97], v[244:247], v[204:207], v[94:97]
	v_mfma_f32_16x16x32_bf16 v[10:13], v[240:243], v[184:187], v[10:13]
	s_waitcnt lgkmcnt(0)
	v_mfma_f32_16x16x32_bf16 v[22:25], v[248:251], v[184:187], v[22:25]
	v_mfma_f32_16x16x32_bf16 v[34:37], v[240:243], v[192:195], v[34:37]
	v_mfma_f32_16x16x32_bf16 v[46:49], v[248:251], v[192:195], v[46:49]
	v_mfma_f32_16x16x32_bf16 v[58:61], v[240:243], v[200:203], v[58:61]
	v_mfma_f32_16x16x32_bf16 v[70:73], v[248:251], v[200:203], v[70:73]
	v_mfma_f32_16x16x32_bf16 v[82:85], v[240:243], v[210:213], v[82:85]
	v_mfma_f32_16x16x32_bf16 v[94:97], v[248:251], v[210:213], v[94:97]
	s_setprio 0
	v_readfirstlane_b32 s12, v147
	s_addk_i32 s28, 0x180
	s_mov_b32 m0, s12
	v_readfirstlane_b32 s12, v148
	s_barrier
	ds_read_b128 v[180:183], v141 offset:49152
	ds_read_b128 v[184:187], v141 offset:50176
	ds_read_b128 v[188:191], v140 offset:49152
	ds_read_b128 v[192:195], v140 offset:50176
	ds_read_b128 v[196:199], v139 offset:49152
	ds_read_b128 v[200:203], v139 offset:50176
	ds_read_b128 v[204:207], v138 offset:49152
	ds_read_b128 v[210:213], v138 offset:50176
	buffer_load_dwordx4 v130, s[4:7], s28 offen lds
	s_addk_i32 s29, 0x180
	s_mov_b32 m0, s12
	s_nop 0
	buffer_load_dwordx4 v130, s[4:7], s29 offen lds
	s_barrier
; #define WAIT_V(n) asm volatile("s_waitcnt vmcnt(" #n ")" ::: "memory")
; #define WAIT_L(n) asm volatile("s_waitcnt lgkmcnt(" #n ")" ::: "memory")
; #define BAR __builtin_amdgcn_s_barrier()
; #define SCHED __builtin_amdgcn_sched_barrier(0)
; template <int MODE>
; __device__ __forceinline__ void gemm_tile(const int ph, const int which, const int pm, const int pn) {
;     ...
;     BAR; WAIT_L(0); MMA(1, 0, At, B0); BAR; SCHED;
;     STAGE(SB(1, 1), RB, bcolB, t + 3);
;     WAIT_V(6); BAR; MMA(1, 1, At, B1); BAR;
;   }
;   {
;     LDB(B0, 0, 0); LDA(At, 0, 0); STAGE(SA(1, 1), RA, brow + HALF, nt - 1);
;     BAR; WAIT_L(0); MMA(0, 0, At, B0); BAR;
	s_waitcnt lgkmcnt(0)
	s_setprio 1
	s_waitcnt lgkmcnt(7)
	v_mfma_f32_16x16x32_bf16 v[14:17], v[156:159], v[180:183], v[14:17]
	v_mfma_f32_16x16x32_bf16 v[26:29], v[172:175], v[180:183], v[26:29]
	s_waitcnt lgkmcnt(5)
	v_mfma_f32_16x16x32_bf16 v[38:41], v[156:159], v[188:191], v[38:41]
	v_mfma_f32_16x16x32_bf16 v[50:53], v[172:175], v[188:191], v[50:53]
	s_waitcnt lgkmcnt(3)
	v_mfma_f32_16x16x32_bf16 v[62:65], v[156:159], v[196:199], v[62:65]
	v_mfma_f32_16x16x32_bf16 v[74:77], v[172:175], v[196:199], v[74:77]
	s_waitcnt lgkmcnt(1)
	v_mfma_f32_16x16x32_bf16 v[86:89], v[156:159], v[204:207], v[86:89]
	v_mfma_f32_16x16x32_bf16 v[98:101], v[172:175], v[204:207], v[98:101]
	v_mfma_f32_16x16x32_bf16 v[14:17], v[168:171], v[184:187], v[14:17]
	v_mfma_f32_16x16x32_bf16 v[26:29], v[176:179], v[184:187], v[26:29]
	v_mfma_f32_16x16x32_bf16 v[38:41], v[168:171], v[192:195], v[38:41]
	v_mfma_f32_16x16x32_bf16 v[50:53], v[176:179], v[192:195], v[50:53]
	v_mfma_f32_16x16x32_bf16 v[62:65], v[168:171], v[200:203], v[62:65]
	v_mfma_f32_16x16x32_bf16 v[74:77], v[176:179], v[200:203], v[74:77]
	s_waitcnt lgkmcnt(0)
	v_mfma_f32_16x16x32_bf16 v[86:89], v[168:171], v[210:213], v[86:89]
	v_mfma_f32_16x16x32_bf16 v[98:101], v[176:179], v[210:213], v[98:101]
	s_setprio 0
	s_barrier
	v_readfirstlane_b32 s12, v150
	s_addk_i32 s38, 0x180
	s_mov_b32 m0, s12
	v_readfirstlane_b32 s12, v152
	buffer_load_dwordx4 v130, s[68:71], s38 offen lds
	s_addk_i32 s43, 0x180
	s_mov_b32 m0, s12
	s_nop 0
	buffer_load_dwordx4 v130, s[68:71], s43 offen lds
	s_waitcnt vmcnt(6)
	s_barrier
	s_setprio 1
	v_mfma_f32_16x16x32_bf16 v[90:93], v[236:239], v[180:183], v[90:93]
	v_mfma_f32_16x16x32_bf16 v[102:105], v[244:247], v[180:183], v[102:105]
	v_mfma_f32_16x16x32_bf16 v[106:109], v[236:239], v[188:191], v[106:109]
	v_mfma_f32_16x16x32_bf16 v[110:113], v[244:247], v[188:191], v[110:113]
	v_mfma_f32_16x16x32_bf16 v[114:117], v[236:239], v[196:199], v[114:117]
	v_mfma_f32_16x16x32_bf16 v[118:121], v[244:247], v[196:199], v[118:121]
	v_mfma_f32_16x16x32_bf16 v[122:125], v[236:239], v[204:207], v[122:125]
	v_mfma_f32_16x16x32_bf16 v[126:129], v[244:247], v[204:207], v[126:129]
	v_mfma_f32_16x16x32_bf16 v[90:93], v[240:243], v[184:187], v[90:93]
	v_mfma_f32_16x16x32_bf16 v[102:105], v[248:251], v[184:187], v[102:105]
	v_mfma_f32_16x16x32_bf16 v[106:109], v[240:243], v[192:195], v[106:109]
	v_mfma_f32_16x16x32_bf16 v[110:113], v[248:251], v[192:195], v[110:113]
	v_mfma_f32_16x16x32_bf16 v[114:117], v[240:243], v[200:203], v[114:117]
	v_mfma_f32_16x16x32_bf16 v[118:121], v[248:251], v[200:203], v[118:121]
	v_mfma_f32_16x16x32_bf16 v[122:125], v[240:243], v[210:213], v[122:125]
	v_mfma_f32_16x16x32_bf16 v[126:129], v[248:251], v[210:213], v[126:129]
	s_setprio 0
	s_addk_i32 s21, 0x100
	s_cmp_lt_u32 s22, s2
	s_cbranch_scc1 .Lgemm_head_370
	s_barrier
	s_add_i32 s2, s26, s9
	s_lshl_b32 s2, s2, 1
	v_readfirstlane_b32 s3, v151
	s_addk_i32 s2, 0xff80
	s_mov_b32 s6, s70
	s_mov_b32 s7, s71
	s_mov_b32 m0, s3
	v_readfirstlane_b32 s3, v149
	ds_read_b128 v[132:135], v154
	ds_read_b128 v[144:147], v154 offset:1024
	ds_read_b128 v[156:159], v154 offset:2048
	ds_read_b128 v[168:171], v154 offset:3072
	ds_read_b128 v[172:175], v141
	ds_read_b128 v[176:179], v141 offset:1024
	ds_read_b128 v[180:183], v140
	ds_read_b128 v[184:187], v140 offset:1024
	ds_read_b128 v[188:191], v139
	ds_read_b128 v[192:195], v139 offset:1024
	ds_read_b128 v[196:199], v138
	ds_read_b128 v[200:203], v138 offset:1024
	buffer_load_dwordx4 v130, s[4:7], s2 offen lds
	s_add_i32 s2, s2, s8
	s_mov_b32 m0, s3
	s_nop 0
	buffer_load_dwordx4 v130, s[4:7], s2 offen lds
	s_barrier
	s_waitcnt lgkmcnt(0)
	s_setprio 1
	s_waitcnt lgkmcnt(7)
	v_mfma_f32_16x16x32_bf16 v[2:5], v[132:135], v[172:175], v[2:5]
	v_mfma_f32_16x16x32_bf16 v[6:9], v[156:159], v[172:175], v[6:9]
	s_waitcnt lgkmcnt(5)
	v_mfma_f32_16x16x32_bf16 v[18:21], v[132:135], v[180:183], v[18:21]
	s_waitcnt lgkmcnt(1)
	v_mfma_f32_16x16x32_bf16 v[66:69], v[132:135], v[196:199], v[66:69]
	v_mfma_f32_16x16x32_bf16 v[78:81], v[156:159], v[196:199], v[78:81]
	v_mfma_f32_16x16x32_bf16 v[2:5], v[144:147], v[176:179], v[2:5]
	v_mfma_f32_16x16x32_bf16 v[6:9], v[168:171], v[176:179], v[6:9]
	v_mfma_f32_16x16x32_bf16 v[18:21], v[144:147], v[184:187], v[18:21]
	v_mfma_f32_16x16x32_bf16 v[30:33], v[156:159], v[180:183], v[30:33]
	v_mfma_f32_16x16x32_bf16 v[42:45], v[132:135], v[188:191], v[42:45]
	v_mfma_f32_16x16x32_bf16 v[54:57], v[156:159], v[188:191], v[54:57]
	s_waitcnt lgkmcnt(0)
	v_mfma_f32_16x16x32_bf16 v[66:69], v[144:147], v[200:203], v[66:69]
	v_mfma_f32_16x16x32_bf16 v[78:81], v[168:171], v[200:203], v[78:81]
	v_mfma_f32_16x16x32_bf16 v[30:33], v[168:171], v[184:187], v[30:33]
	v_mfma_f32_16x16x32_bf16 v[42:45], v[144:147], v[192:195], v[42:45]
	v_mfma_f32_16x16x32_bf16 v[54:57], v[168:171], v[192:195], v[54:57]
	s_setprio 0
	s_barrier
	ds_read_b128 v[148:151], v153
	ds_read_b128 v[204:207], v153 offset:1024
	ds_read_b128 v[210:213], v153 offset:2048
	ds_read_b128 v[152:155], v153 offset:3072
	s_barrier
; #define WAIT_V(n) asm volatile("s_waitcnt vmcnt(" #n ")" ::: "memory")
; #define WAIT_L(n) asm volatile("s_waitcnt lgkmcnt(" #n ")" ::: "memory")
; #define BAR __builtin_amdgcn_s_barrier()
; template <int MODE>
; __device__ __forceinline__ void gemm_tile(const int ph, const int which, const int pm, const int pn) {
;     ...
;     LDB(B1, 0, 1); BAR; WAIT_L(0); MMA(0, 1, At, B1); BAR;
;     LDA(At, 0, 1); WAIT_V(4); BAR; WAIT_L(0); MMA(1, 0, At, B0); MMA(1, 1, At, B1); BAR;
;   }
;   {
;     LDB(B0, 1, 0); LDA(At, 1, 0); WAIT_V(2); BAR; WAIT_L(0); MMA(0, 0, At, B0); BAR;
	s_waitcnt lgkmcnt(0)
	s_setprio 1
	s_waitcnt lgkmcnt(3)
	v_mfma_f32_16x16x32_bf16 v[10:13], v[148:151], v[172:175], v[10:13]
	s_waitcnt lgkmcnt(1)
	v_mfma_f32_16x16x32_bf16 v[22:25], v[210:213], v[172:175], v[22:25]
	v_mfma_f32_16x16x32_bf16 v[58:61], v[148:151], v[188:191], v[58:61]
	v_mfma_f32_16x16x32_bf16 v[70:73], v[210:213], v[188:191], v[70:73]
	v_mfma_f32_16x16x32_bf16 v[82:85], v[148:151], v[196:199], v[82:85]
	v_mfma_f32_16x16x32_bf16 v[10:13], v[204:207], v[176:179], v[10:13]
	s_waitcnt lgkmcnt(0)
	v_mfma_f32_16x16x32_bf16 v[22:25], v[152:155], v[176:179], v[22:25]
	v_mfma_f32_16x16x32_bf16 v[34:37], v[148:151], v[180:183], v[34:37]
	v_mfma_f32_16x16x32_bf16 v[46:49], v[210:213], v[180:183], v[46:49]
	v_mfma_f32_16x16x32_bf16 v[58:61], v[204:207], v[192:195], v[58:61]
	v_mfma_f32_16x16x32_bf16 v[70:73], v[152:155], v[192:195], v[70:73]
	v_mfma_f32_16x16x32_bf16 v[172:175], v[204:207], v[200:203], v[82:85]
	v_mfma_f32_16x16x32_bf16 v[82:85], v[210:213], v[196:199], v[94:97]
	v_mfma_f32_16x16x32_bf16 v[34:37], v[204:207], v[184:187], v[34:37]
	v_mfma_f32_16x16x32_bf16 v[46:49], v[152:155], v[184:187], v[46:49]
	v_mfma_f32_16x16x32_bf16 v[176:179], v[152:155], v[200:203], v[82:85]
	s_setprio 0
	s_barrier
	s_nop 2
	ds_read_b128 v[82:85], v141 offset:16384
	ds_read_b128 v[94:97], v141 offset:17408
	ds_read_b128 v[180:183], v140 offset:16384
	ds_read_b128 v[184:187], v140 offset:17408
	ds_read_b128 v[188:191], v139 offset:16384
	ds_read_b128 v[192:195], v139 offset:17408
	ds_read_b128 v[196:199], v138 offset:16384
	ds_read_b128 v[200:203], v138 offset:17408
	s_waitcnt vmcnt(4)
	s_barrier
	s_waitcnt lgkmcnt(0)
	s_setprio 1
	s_waitcnt lgkmcnt(3)
	v_mfma_f32_16x16x32_bf16 v[74:77], v[156:159], v[188:191], v[74:77]
	s_waitcnt lgkmcnt(2)
	v_mfma_f32_16x16x32_bf16 v[236:239], v[168:171], v[192:195], v[74:77]
	s_waitcnt lgkmcnt(1)
	v_mfma_f32_16x16x32_bf16 v[74:77], v[132:135], v[196:199], v[86:89]
	v_mfma_f32_16x16x32_bf16 v[14:17], v[132:135], v[82:85], v[14:17]
	v_mfma_f32_16x16x32_bf16 v[62:65], v[132:135], v[188:191], v[62:65]
	s_waitcnt lgkmcnt(0)
	v_mfma_f32_16x16x32_bf16 v[240:243], v[144:147], v[200:203], v[74:77]
	v_mfma_f32_16x16x32_bf16 v[74:77], v[156:159], v[196:199], v[98:101]
	v_mfma_f32_16x16x32_bf16 v[14:17], v[144:147], v[94:97], v[14:17]
	v_mfma_f32_16x16x32_bf16 v[26:29], v[156:159], v[82:85], v[26:29]
	v_mfma_f32_16x16x32_bf16 v[38:41], v[132:135], v[180:183], v[38:41]
	v_mfma_f32_16x16x32_bf16 v[50:53], v[156:159], v[180:183], v[50:53]
	v_mfma_f32_16x16x32_bf16 v[62:65], v[144:147], v[192:195], v[62:65]
	v_mfma_f32_16x16x32_bf16 v[98:101], v[168:171], v[200:203], v[74:77]
	v_mfma_f32_16x16x32_bf16 v[26:29], v[168:171], v[94:97], v[26:29]
	v_mfma_f32_16x16x32_bf16 v[38:41], v[144:147], v[184:187], v[38:41]
	v_mfma_f32_16x16x32_bf16 v[50:53], v[168:171], v[184:187], v[50:53]
	v_mfma_f32_16x16x32_bf16 v[74:77], v[148:151], v[82:85], v[90:93]
	v_mfma_f32_16x16x32_bf16 v[168:171], v[204:207], v[94:97], v[74:77]
	v_mfma_f32_16x16x32_bf16 v[74:77], v[210:213], v[82:85], v[102:105]
	v_mfma_f32_16x16x32_bf16 v[244:247], v[152:155], v[94:97], v[74:77]
	v_mfma_f32_16x16x32_bf16 v[74:77], v[148:151], v[180:183], v[106:109]
	v_mfma_f32_16x16x32_bf16 v[248:251], v[204:207], v[184:187], v[74:77]
	v_mfma_f32_16x16x32_bf16 v[74:77], v[210:213], v[180:183], v[110:113]
	v_mfma_f32_16x16x32_bf16 v[180:183], v[152:155], v[184:187], v[74:77]
	v_mfma_f32_16x16x32_bf16 v[74:77], v[148:151], v[188:191], v[114:117]
	v_mfma_f32_16x16x32_bf16 v[184:187], v[204:207], v[192:195], v[74:77]
	v_mfma_f32_16x16x32_bf16 v[74:77], v[210:213], v[188:191], v[118:121]
	v_mfma_f32_16x16x32_bf16 v[188:191], v[152:155], v[192:195], v[74:77]
	v_mfma_f32_16x16x32_bf16 v[74:77], v[148:151], v[196:199], v[122:125]
	v_mfma_f32_16x16x32_bf16 v[192:195], v[204:207], v[200:203], v[74:77]
	v_mfma_f32_16x16x32_bf16 v[74:77], v[210:213], v[196:199], v[126:129]
	v_mfma_f32_16x16x32_bf16 v[196:199], v[152:155], v[200:203], v[74:77]
	s_setprio 0
	s_barrier
	ds_read_b128 v[102:105], v137
	ds_read_b128 v[200:203], v137 offset:1024
	ds_read_b128 v[204:207], v137 offset:2048
	ds_read_b128 v[210:213], v137 offset:3072
	s_nop 0
	ds_read_b128 v[74:77], v141 offset:32768
	ds_read_b128 v[82:85], v141 offset:33792
	ds_read_b128 v[144:147], v140 offset:32768
	ds_read_b128 v[148:151], v140 offset:33792
	ds_read_b128 v[152:155], v139 offset:32768
	ds_read_b128 v[156:159], v139 offset:33792
	ds_read_b128 v[218:221], v138 offset:32768
	ds_read_b128 v[230:233], v138 offset:33792
	s_waitcnt vmcnt(2)
	s_barrier
; #define WAIT_V(n) asm volatile("s_waitcnt vmcnt(" #n ")" ::: "memory")
; #define WAIT_L(n) asm volatile("s_waitcnt lgkmcnt(" #n ")" ::: "memory")
; #define BAR __builtin_amdgcn_s_barrier()
; template <int MODE>
; __device__ __forceinline__ void gemm_tile(const int ph, const int which, const int pm, const int pn) {
;     ...
;     LDB(B0, 1, 0); LDA(At, 1, 0); WAIT_V(2); BAR; WAIT_L(0); MMA(0, 0, At, B0); BAR;
;     LDB(B1, 1, 1); WAIT_V(0); BAR; WAIT_L(0); MMA(0, 1, At, B1); BAR;
;     LDA(At, 1, 1); BAR; WAIT_L(0); MMA(1, 0, At, B0); MMA(1, 1, At, B1); BAR;
;   }
;   if (wr == 0) BAR;
	s_waitcnt lgkmcnt(0)
	s_setprio 1
	s_waitcnt lgkmcnt(7)
	v_mfma_f32_16x16x32_bf16 v[2:5], v[102:105], v[74:77], v[2:5]
	s_waitcnt lgkmcnt(6)
	v_mfma_f32_16x16x32_bf16 v[106:109], v[200:203], v[82:85], v[2:5]
	v_mfma_f32_16x16x32_bf16 v[2:5], v[204:207], v[74:77], v[6:9]
	v_mfma_f32_16x16x32_bf16 v[110:113], v[210:213], v[82:85], v[2:5]
	s_waitcnt lgkmcnt(5)
	v_mfma_f32_16x16x32_bf16 v[2:5], v[102:105], v[144:147], v[18:21]
	s_waitcnt lgkmcnt(4)
	v_mfma_f32_16x16x32_bf16 v[114:117], v[200:203], v[148:151], v[2:5]
	v_mfma_f32_16x16x32_bf16 v[2:5], v[204:207], v[144:147], v[30:33]
	v_mfma_f32_16x16x32_bf16 v[118:121], v[210:213], v[148:151], v[2:5]
	s_waitcnt lgkmcnt(3)
	v_mfma_f32_16x16x32_bf16 v[2:5], v[102:105], v[152:155], v[42:45]
	s_waitcnt lgkmcnt(2)
	v_mfma_f32_16x16x32_bf16 v[122:125], v[200:203], v[156:159], v[2:5]
	v_mfma_f32_16x16x32_bf16 v[2:5], v[204:207], v[152:155], v[54:57]
	v_mfma_f32_16x16x32_bf16 v[126:129], v[210:213], v[156:159], v[2:5]
	s_waitcnt lgkmcnt(1)
	v_mfma_f32_16x16x32_bf16 v[2:5], v[102:105], v[218:221], v[66:69]
	s_waitcnt lgkmcnt(0)
	v_mfma_f32_16x16x32_bf16 v[130:133], v[200:203], v[230:233], v[2:5]
	v_mfma_f32_16x16x32_bf16 v[2:5], v[204:207], v[218:221], v[78:81]
	v_mfma_f32_16x16x32_bf16 v[134:137], v[210:213], v[230:233], v[2:5]
	s_setprio 0
	s_barrier
	s_nop 4
	ds_read_b128 v[2:5], v142
	ds_read_b128 v[6:9], v142 offset:1024
	ds_read_b128 v[30:33], v142 offset:2048
	ds_read_b128 v[42:45], v142 offset:3072
	s_waitcnt vmcnt(0)
	s_barrier
	s_waitcnt lgkmcnt(0)
	s_setprio 1
	s_waitcnt lgkmcnt(3)
	v_mfma_f32_16x16x32_bf16 v[10:13], v[2:5], v[74:77], v[10:13]
	s_waitcnt lgkmcnt(2)
	v_mfma_f32_16x16x32_bf16 v[94:97], v[6:9], v[82:85], v[10:13]
	s_waitcnt lgkmcnt(1)
	v_mfma_f32_16x16x32_bf16 v[10:13], v[30:33], v[74:77], v[22:25]
	s_waitcnt lgkmcnt(0)
	v_mfma_f32_16x16x32_bf16 v[90:93], v[42:45], v[82:85], v[10:13]
	v_mfma_f32_16x16x32_bf16 v[10:13], v[2:5], v[144:147], v[34:37]
	v_mfma_f32_16x16x32_bf16 v[86:89], v[6:9], v[148:151], v[10:13]
	v_mfma_f32_16x16x32_bf16 v[10:13], v[30:33], v[144:147], v[46:49]
	v_mfma_f32_16x16x32_bf16 v[82:85], v[42:45], v[148:151], v[10:13]
	v_mfma_f32_16x16x32_bf16 v[10:13], v[2:5], v[152:155], v[58:61]
	v_mfma_f32_16x16x32_bf16 v[78:81], v[6:9], v[156:159], v[10:13]
	v_mfma_f32_16x16x32_bf16 v[10:13], v[30:33], v[152:155], v[70:73]
	v_mfma_f32_16x16x32_bf16 v[74:77], v[42:45], v[156:159], v[10:13]
	v_mfma_f32_16x16x32_bf16 v[10:13], v[2:5], v[218:221], v[172:175]
	v_mfma_f32_16x16x32_bf16 v[70:73], v[6:9], v[230:233], v[10:13]
	v_mfma_f32_16x16x32_bf16 v[10:13], v[30:33], v[218:221], v[176:179]
	v_mfma_f32_16x16x32_bf16 v[66:69], v[42:45], v[230:233], v[10:13]
	s_setprio 0
	s_barrier
	s_nop 4
	ds_read_b128 v[10:13], v141 offset:49152
	ds_read_b128 v[18:21], v141 offset:50176
	ds_read_b128 v[34:37], v140 offset:49152
	ds_read_b128 v[46:49], v140 offset:50176
	ds_read_b128 v[54:57], v139 offset:49152
	ds_read_b128 v[172:175], v139 offset:50176
	ds_read_b128 v[176:179], v138 offset:49152
	ds_read_b128 v[218:221], v138 offset:50176
	s_barrier
	s_waitcnt lgkmcnt(0)
	s_setprio 1
	s_waitcnt lgkmcnt(7)
	v_mfma_f32_16x16x32_bf16 v[14:17], v[102:105], v[10:13], v[14:17]
	s_waitcnt lgkmcnt(6)
	v_mfma_f32_16x16x32_bf16 v[158:161], v[200:203], v[18:21], v[14:17]
	v_mfma_f32_16x16x32_bf16 v[14:17], v[204:207], v[10:13], v[26:29]
	v_mfma_f32_16x16x32_bf16 v[154:157], v[210:213], v[18:21], v[14:17]
	s_waitcnt lgkmcnt(5)
	v_mfma_f32_16x16x32_bf16 v[14:17], v[102:105], v[34:37], v[38:41]
	s_waitcnt lgkmcnt(4)
	v_mfma_f32_16x16x32_bf16 v[150:153], v[200:203], v[46:49], v[14:17]
	v_mfma_f32_16x16x32_bf16 v[14:17], v[204:207], v[34:37], v[50:53]
	v_mfma_f32_16x16x32_bf16 v[146:149], v[210:213], v[46:49], v[14:17]
	s_waitcnt lgkmcnt(3)
	v_mfma_f32_16x16x32_bf16 v[14:17], v[102:105], v[54:57], v[62:65]
	s_waitcnt lgkmcnt(2)
	v_mfma_f32_16x16x32_bf16 v[142:145], v[200:203], v[172:175], v[14:17]
	v_mfma_f32_16x16x32_bf16 v[14:17], v[204:207], v[54:57], v[236:239]
	v_mfma_f32_16x16x32_bf16 v[138:141], v[210:213], v[172:175], v[14:17]
	s_waitcnt lgkmcnt(1)
	v_mfma_f32_16x16x32_bf16 v[14:17], v[102:105], v[176:179], v[240:243]
	s_waitcnt lgkmcnt(0)
	v_mfma_f32_16x16x32_bf16 v[102:105], v[200:203], v[218:221], v[14:17]
	v_mfma_f32_16x16x32_bf16 v[14:17], v[204:207], v[176:179], v[98:101]
	v_mfma_f32_16x16x32_bf16 v[98:101], v[210:213], v[218:221], v[14:17]
	v_mfma_f32_16x16x32_bf16 v[14:17], v[2:5], v[10:13], v[168:171]
	v_mfma_f32_16x16x32_bf16 v[10:13], v[30:33], v[10:13], v[244:247]
	v_mfma_f32_16x16x32_bf16 v[58:61], v[42:45], v[18:21], v[10:13]
	v_mfma_f32_16x16x32_bf16 v[10:13], v[2:5], v[34:37], v[248:251]
	v_mfma_f32_16x16x32_bf16 v[22:25], v[6:9], v[46:49], v[10:13]
	v_mfma_f32_16x16x32_bf16 v[10:13], v[30:33], v[34:37], v[180:183]
	v_mfma_f32_16x16x32_bf16 v[62:65], v[6:9], v[18:21], v[14:17]
	v_mfma_f32_16x16x32_bf16 v[18:21], v[42:45], v[46:49], v[10:13]
	v_mfma_f32_16x16x32_bf16 v[10:13], v[2:5], v[54:57], v[184:187]
	v_mfma_f32_16x16x32_bf16 v[2:5], v[2:5], v[176:179], v[192:195]
	v_mfma_f32_16x16x32_bf16 v[14:17], v[6:9], v[172:175], v[10:13]
	v_mfma_f32_16x16x32_bf16 v[10:13], v[30:33], v[54:57], v[188:191]
	v_mfma_f32_16x16x32_bf16 v[6:9], v[6:9], v[218:221], v[2:5]
	v_mfma_f32_16x16x32_bf16 v[2:5], v[30:33], v[176:179], v[196:199]
	v_mfma_f32_16x16x32_bf16 v[10:13], v[42:45], v[172:175], v[10:13]
	v_mfma_f32_16x16x32_bf16 v[2:5], v[42:45], v[218:221], v[2:5]
	s_setprio 0
	s_movk_i32 s2, 0x100
	v_cmp_gt_u32_e32 vcc, s2, v164
	s_barrier
	s_and_saveexec_b64 s[2:3], vcc
	s_cbranch_execz .LBB0_373
	s_barrier

; #define WAIT_L(n) asm volatile("s_waitcnt lgkmcnt(" #n ")" ::: "memory")
; #define BAR __builtin_amdgcn_s_barrier()
; #define SCHED __builtin_amdgcn_sched_barrier(0)
; template <int MODE>
; __device__ __forceinline__ void gemm_tile(const int ph, const int which, const int pm, const int pn) {
;     ...
;     LDB(B0, 0, 0); SCHED; LDA(At, 0, 0); STAGE(SA(1, 1), RA, brow + HALF, t + 1);
;     WAIT_L(8); BAR; WAIT_L(0); MMA(0, 0, At, B0); BAR; SCHED;
;     LDB(B1, 0, 1); STAGE(SB(0, 0), RB, bcol, t + 2);
;     BAR; WAIT_L(0); MMA(0, 1, At, B1); BAR;
;     LDA(At, 0, 1); STAGE(SA(0, 0), RA, brow, t + 2);
;     BAR; WAIT_L(0); MMA(1, 0, At, B0); BAR; SCHED;
.LBB0_540:
	ds_read_b128 v[158:161], v156
	ds_read_b128 v[162:165], v156 offset:1024
	ds_read_b128 v[166:169], v156 offset:2048
	ds_read_b128 v[170:173], v156 offset:3072
	s_add_i32 s26, s10, s23
	v_readfirstlane_b32 s28, v153
	s_add_i32 s27, s26, 0x80
	s_mov_b32 m0, s28
	ds_read_b128 v[174:177], v135
	ds_read_b128 v[178:181], v135 offset:1024
	ds_read_b128 v[182:185], v134
	ds_read_b128 v[186:189], v134 offset:1024
	ds_read_b128 v[190:193], v133
	ds_read_b128 v[194:197], v133 offset:1024
	ds_read_b128 v[198:201], v132
	ds_read_b128 v[202:205], v132 offset:1024
	buffer_load_dwordx4 v136, s[4:7], s27 offen lds
	s_add_i32 s27, s3, s23
	v_readfirstlane_b32 s51, v151
	s_add_i32 s28, s27, 0x80
	s_mov_b32 m0, s51
	s_nop 0
	buffer_load_dwordx4 v136, s[4:7], s28 offen lds
	s_waitcnt lgkmcnt(8)
	s_barrier
	s_waitcnt lgkmcnt(0)
	s_setprio 1
	s_waitcnt lgkmcnt(7)
	v_mfma_f32_16x16x32_bf16 v[126:129], v[158:161], v[174:177], v[126:129]
	v_mfma_f32_16x16x32_bf16 v[122:125], v[166:169], v[174:177], v[122:125]
	s_waitcnt lgkmcnt(5)
	v_mfma_f32_16x16x32_bf16 v[118:121], v[158:161], v[182:185], v[118:121]
	v_mfma_f32_16x16x32_bf16 v[114:117], v[166:169], v[182:185], v[114:117]
	s_waitcnt lgkmcnt(3)
	v_mfma_f32_16x16x32_bf16 v[110:113], v[158:161], v[190:193], v[110:113]
	v_mfma_f32_16x16x32_bf16 v[106:109], v[166:169], v[190:193], v[106:109]
	s_waitcnt lgkmcnt(1)
	v_mfma_f32_16x16x32_bf16 v[102:105], v[158:161], v[198:201], v[102:105]
	v_mfma_f32_16x16x32_bf16 v[98:101], v[166:169], v[198:201], v[98:101]
	v_mfma_f32_16x16x32_bf16 v[126:129], v[162:165], v[178:181], v[126:129]
	v_mfma_f32_16x16x32_bf16 v[122:125], v[170:173], v[178:181], v[122:125]
	v_mfma_f32_16x16x32_bf16 v[118:121], v[162:165], v[186:189], v[118:121]
	v_mfma_f32_16x16x32_bf16 v[114:117], v[170:173], v[186:189], v[114:117]
	v_mfma_f32_16x16x32_bf16 v[110:113], v[162:165], v[194:197], v[110:113]
	v_mfma_f32_16x16x32_bf16 v[106:109], v[170:173], v[194:197], v[106:109]
	s_waitcnt lgkmcnt(0)
	v_mfma_f32_16x16x32_bf16 v[102:105], v[162:165], v[202:205], v[102:105]
	v_mfma_f32_16x16x32_bf16 v[98:101], v[170:173], v[202:205], v[98:101]
	s_setprio 0
	s_barrier
	s_add_i32 s28, s22, s23
	v_readfirstlane_b32 s84, v139
	s_add_i32 s51, s28, 0x100
	s_mov_b32 m0, s84
	ds_read_b128 v[236:239], v155
	ds_read_b128 v[240:243], v155 offset:1024
	ds_read_b128 v[244:247], v155 offset:2048
	ds_read_b128 v[248:251], v155 offset:3072
	buffer_load_dwordx4 v136, s[68:71], s51 offen lds
	s_add_i32 s51, s21, s23
	v_readfirstlane_b32 s50, v140
	s_add_i32 s84, s51, 0x100
	s_mov_b32 m0, s50
	s_add_i32 s25, s25, 2
	buffer_load_dwordx4 v136, s[68:71], s84 offen lds
	s_barrier
	s_waitcnt lgkmcnt(0)
	s_setprio 1
	s_waitcnt lgkmcnt(3)
	v_mfma_f32_16x16x32_bf16 v[94:97], v[236:239], v[174:177], v[94:97]
	s_waitcnt lgkmcnt(1)
	v_mfma_f32_16x16x32_bf16 v[90:93], v[244:247], v[174:177], v[90:93]
	v_mfma_f32_16x16x32_bf16 v[86:89], v[236:239], v[182:185], v[86:89]
	v_mfma_f32_16x16x32_bf16 v[82:85], v[244:247], v[182:185], v[82:85]
	v_mfma_f32_16x16x32_bf16 v[78:81], v[236:239], v[190:193], v[78:81]
	v_mfma_f32_16x16x32_bf16 v[74:77], v[244:247], v[190:193], v[74:77]
	v_mfma_f32_16x16x32_bf16 v[70:73], v[236:239], v[198:201], v[70:73]
	v_mfma_f32_16x16x32_bf16 v[66:69], v[244:247], v[198:201], v[66:69]
	v_mfma_f32_16x16x32_bf16 v[94:97], v[240:243], v[178:181], v[94:97]
	s_waitcnt lgkmcnt(0)
	v_mfma_f32_16x16x32_bf16 v[90:93], v[248:251], v[178:181], v[90:93]
	v_mfma_f32_16x16x32_bf16 v[86:89], v[240:243], v[186:189], v[86:89]
	v_mfma_f32_16x16x32_bf16 v[82:85], v[248:251], v[186:189], v[82:85]
	v_mfma_f32_16x16x32_bf16 v[78:81], v[240:243], v[194:197], v[78:81]
	v_mfma_f32_16x16x32_bf16 v[74:77], v[248:251], v[194:197], v[74:77]
	v_mfma_f32_16x16x32_bf16 v[70:73], v[240:243], v[202:205], v[70:73]
	v_mfma_f32_16x16x32_bf16 v[66:69], v[248:251], v[202:205], v[66:69]
	s_setprio 0
	s_add_i32 s50, s20, s23
	v_readfirstlane_b32 s29, v137
	s_add_i32 s84, s50, 0x100
	s_mov_b32 m0, s29
	s_add_i32 s29, s19, s23
	v_readfirstlane_b32 s43, v141
	s_barrier
	ds_read_b128 v[174:177], v135 offset:16384
	ds_read_b128 v[178:181], v135 offset:17408
	ds_read_b128 v[182:185], v134 offset:16384
	ds_read_b128 v[186:189], v134 offset:17408
	ds_read_b128 v[190:193], v133 offset:16384
	ds_read_b128 v[194:197], v133 offset:17408
	ds_read_b128 v[198:201], v132 offset:16384
	ds_read_b128 v[202:205], v132 offset:17408
	buffer_load_dwordx4 v136, s[4:7], s84 offen lds
	s_add_i32 s84, s29, 0x100
	s_mov_b32 m0, s43
	s_nop 0
	buffer_load_dwordx4 v136, s[4:7], s84 offen lds
	s_barrier
	s_waitcnt lgkmcnt(0)
	s_setprio 1
	s_waitcnt lgkmcnt(7)
	v_mfma_f32_16x16x32_bf16 v[62:65], v[158:161], v[174:177], v[62:65]
	v_mfma_f32_16x16x32_bf16 v[58:61], v[166:169], v[174:177], v[58:61]
	s_waitcnt lgkmcnt(5)
	v_mfma_f32_16x16x32_bf16 v[54:57], v[158:161], v[182:185], v[54:57]
	v_mfma_f32_16x16x32_bf16 v[50:53], v[166:169], v[182:185], v[50:53]
	s_waitcnt lgkmcnt(3)
	v_mfma_f32_16x16x32_bf16 v[46:49], v[158:161], v[190:193], v[46:49]
	v_mfma_f32_16x16x32_bf16 v[42:45], v[166:169], v[190:193], v[42:45]
	s_waitcnt lgkmcnt(1)
	v_mfma_f32_16x16x32_bf16 v[38:41], v[158:161], v[198:201], v[38:41]
	v_mfma_f32_16x16x32_bf16 v[34:37], v[166:169], v[198:201], v[34:37]
	v_mfma_f32_16x16x32_bf16 v[62:65], v[162:165], v[178:181], v[62:65]
	v_mfma_f32_16x16x32_bf16 v[58:61], v[170:173], v[178:181], v[58:61]
	v_mfma_f32_16x16x32_bf16 v[54:57], v[162:165], v[186:189], v[54:57]
	v_mfma_f32_16x16x32_bf16 v[50:53], v[170:173], v[186:189], v[50:53]
	v_mfma_f32_16x16x32_bf16 v[46:49], v[162:165], v[194:197], v[46:49]
	v_mfma_f32_16x16x32_bf16 v[42:45], v[170:173], v[194:197], v[42:45]
	s_waitcnt lgkmcnt(0)
	v_mfma_f32_16x16x32_bf16 v[38:41], v[162:165], v[202:205], v[38:41]
	v_mfma_f32_16x16x32_bf16 v[34:37], v[170:173], v[202:205], v[34:37]
	s_setprio 0
	s_barrier
; #define WAIT_V(n) asm volatile("s_waitcnt vmcnt(" #n ")" ::: "memory")
; #define WAIT_L(n) asm volatile("s_waitcnt lgkmcnt(" #n ")" ::: "memory")
; #define BAR __builtin_amdgcn_s_barrier()
; #define SCHED __builtin_amdgcn_sched_barrier(0)
; template <int MODE>
; __device__ __forceinline__ void gemm_tile(const int ph, const int which, const int pm, const int pn) {
;     ...
;     STAGE(SB(0, 1), RB, bcolB, t + 2);
;     WAIT_V(6); BAR; MMA(1, 1, At, B1); BAR;
;     LDB(B0, 1, 0); SCHED; LDA(At, 1, 0); STAGE(SA(0, 1), RA, brow + HALF, t + 2);
;     WAIT_L(8); BAR; WAIT_L(0); MMA(0, 0, At, B0); BAR; SCHED;
;     LDB(B1, 1, 1); STAGE(SB(1, 0), RB, bcol, t + 3);
;     BAR; WAIT_L(0); MMA(0, 1, At, B1); BAR;
;     LDA(At, 1, 1); STAGE(SA(1, 0), RA, brow, t + 3);
	s_add_i32 s43, s17, s23
	v_readfirstlane_b32 s38, v142
	s_add_i32 s84, s43, 0x100
	s_mov_b32 m0, s38
	s_add_i32 s38, s11, s23
	v_readfirstlane_b32 s12, v143
	buffer_load_dwordx4 v136, s[68:71], s84 offen lds
	s_add_i32 s84, s38, 0x100
	s_mov_b32 m0, s12
	s_nop 0
	buffer_load_dwordx4 v136, s[68:71], s84 offen lds
	s_waitcnt vmcnt(6)
	s_barrier
	s_setprio 1
	v_mfma_f32_16x16x32_bf16 v[30:33], v[236:239], v[174:177], v[30:33]
	v_mfma_f32_16x16x32_bf16 v[26:29], v[244:247], v[174:177], v[26:29]
	v_mfma_f32_16x16x32_bf16 v[22:25], v[236:239], v[182:185], v[22:25]
	v_mfma_f32_16x16x32_bf16 v[18:21], v[244:247], v[182:185], v[18:21]
	v_mfma_f32_16x16x32_bf16 v[14:17], v[236:239], v[190:193], v[14:17]
	v_mfma_f32_16x16x32_bf16 v[10:13], v[244:247], v[190:193], v[10:13]
	v_mfma_f32_16x16x32_bf16 v[6:9], v[236:239], v[198:201], v[6:9]
	v_mfma_f32_16x16x32_bf16 v[2:5], v[244:247], v[198:201], v[2:5]
	v_mfma_f32_16x16x32_bf16 v[30:33], v[240:243], v[178:181], v[30:33]
	v_mfma_f32_16x16x32_bf16 v[26:29], v[248:251], v[178:181], v[26:29]
	v_mfma_f32_16x16x32_bf16 v[22:25], v[240:243], v[186:189], v[22:25]
	v_mfma_f32_16x16x32_bf16 v[18:21], v[248:251], v[186:189], v[18:21]
	v_mfma_f32_16x16x32_bf16 v[14:17], v[240:243], v[194:197], v[14:17]
	v_mfma_f32_16x16x32_bf16 v[10:13], v[248:251], v[194:197], v[10:13]
	v_mfma_f32_16x16x32_bf16 v[6:9], v[240:243], v[202:205], v[6:9]
	v_mfma_f32_16x16x32_bf16 v[2:5], v[248:251], v[202:205], v[2:5]
	s_setprio 0
	s_barrier
	ds_read_b128 v[158:161], v144
	ds_read_b128 v[162:165], v144 offset:1024
	ds_read_b128 v[166:169], v144 offset:2048
	ds_read_b128 v[170:173], v144 offset:3072
	v_readfirstlane_b32 s12, v145
	s_addk_i32 s26, 0x100
	s_mov_b32 m0, s12
	v_readfirstlane_b32 s12, v146
	ds_read_b128 v[174:177], v135 offset:32768
	ds_read_b128 v[178:181], v135 offset:33792
	ds_read_b128 v[182:185], v134 offset:32768
	ds_read_b128 v[186:189], v134 offset:33792
	ds_read_b128 v[190:193], v133 offset:32768
	ds_read_b128 v[194:197], v133 offset:33792
	ds_read_b128 v[198:201], v132 offset:32768
	ds_read_b128 v[202:205], v132 offset:33792
	buffer_load_dwordx4 v136, s[4:7], s26 offen lds
	s_addk_i32 s27, 0x100
	s_mov_b32 m0, s12
	s_nop 0
	buffer_load_dwordx4 v136, s[4:7], s27 offen lds
	s_waitcnt lgkmcnt(8)
	s_barrier
	s_waitcnt lgkmcnt(0)
	s_setprio 1
	s_waitcnt lgkmcnt(7)
	v_mfma_f32_16x16x32_bf16 v[126:129], v[158:161], v[174:177], v[126:129]
	v_mfma_f32_16x16x32_bf16 v[122:125], v[166:169], v[174:177], v[122:125]
	s_waitcnt lgkmcnt(5)
	v_mfma_f32_16x16x32_bf16 v[118:121], v[158:161], v[182:185], v[118:121]
	v_mfma_f32_16x16x32_bf16 v[114:117], v[166:169], v[182:185], v[114:117]
	s_waitcnt lgkmcnt(3)
	v_mfma_f32_16x16x32_bf16 v[110:113], v[158:161], v[190:193], v[110:113]
	v_mfma_f32_16x16x32_bf16 v[106:109], v[166:169], v[190:193], v[106:109]
	s_waitcnt lgkmcnt(1)
	v_mfma_f32_16x16x32_bf16 v[102:105], v[158:161], v[198:201], v[102:105]
	v_mfma_f32_16x16x32_bf16 v[98:101], v[166:169], v[198:201], v[98:101]
	v_mfma_f32_16x16x32_bf16 v[126:129], v[162:165], v[178:181], v[126:129]
	v_mfma_f32_16x16x32_bf16 v[122:125], v[170:173], v[178:181], v[122:125]
	v_mfma_f32_16x16x32_bf16 v[118:121], v[162:165], v[186:189], v[118:121]
	v_mfma_f32_16x16x32_bf16 v[114:117], v[170:173], v[186:189], v[114:117]
	v_mfma_f32_16x16x32_bf16 v[110:113], v[162:165], v[194:197], v[110:113]
	v_mfma_f32_16x16x32_bf16 v[106:109], v[170:173], v[194:197], v[106:109]
	s_waitcnt lgkmcnt(0)
	v_mfma_f32_16x16x32_bf16 v[102:105], v[162:165], v[202:205], v[102:105]
	v_mfma_f32_16x16x32_bf16 v[98:101], v[170:173], v[202:205], v[98:101]
	s_setprio 0
	s_barrier
	v_readfirstlane_b32 s12, v147
	s_addk_i32 s28, 0x180
	s_mov_b32 m0, s12
	v_readfirstlane_b32 s12, v148
	ds_read_b128 v[236:239], v138
	ds_read_b128 v[240:243], v138 offset:1024
	ds_read_b128 v[244:247], v138 offset:2048
	ds_read_b128 v[248:251], v138 offset:3072
	buffer_load_dwordx4 v136, s[68:71], s28 offen lds
	s_addk_i32 s51, 0x180
	s_mov_b32 m0, s12
	s_nop 0
	buffer_load_dwordx4 v136, s[68:71], s51 offen lds
	s_barrier
	s_waitcnt lgkmcnt(0)
	s_setprio 1
	s_waitcnt lgkmcnt(3)
	v_mfma_f32_16x16x32_bf16 v[94:97], v[236:239], v[174:177], v[94:97]
	s_waitcnt lgkmcnt(1)
	v_mfma_f32_16x16x32_bf16 v[90:93], v[244:247], v[174:177], v[90:93]
	v_mfma_f32_16x16x32_bf16 v[86:89], v[236:239], v[182:185], v[86:89]
	v_mfma_f32_16x16x32_bf16 v[82:85], v[244:247], v[182:185], v[82:85]
	v_mfma_f32_16x16x32_bf16 v[78:81], v[236:239], v[190:193], v[78:81]
	v_mfma_f32_16x16x32_bf16 v[74:77], v[244:247], v[190:193], v[74:77]
	v_mfma_f32_16x16x32_bf16 v[70:73], v[236:239], v[198:201], v[70:73]
	v_mfma_f32_16x16x32_bf16 v[66:69], v[244:247], v[198:201], v[66:69]
	v_mfma_f32_16x16x32_bf16 v[94:97], v[240:243], v[178:181], v[94:97]
	s_waitcnt lgkmcnt(0)
	v_mfma_f32_16x16x32_bf16 v[90:93], v[248:251], v[178:181], v[90:93]
	v_mfma_f32_16x16x32_bf16 v[86:89], v[240:243], v[186:189], v[86:89]
	v_mfma_f32_16x16x32_bf16 v[82:85], v[248:251], v[186:189], v[82:85]
	v_mfma_f32_16x16x32_bf16 v[78:81], v[240:243], v[194:197], v[78:81]
	v_mfma_f32_16x16x32_bf16 v[74:77], v[248:251], v[194:197], v[74:77]
	v_mfma_f32_16x16x32_bf16 v[70:73], v[240:243], v[202:205], v[70:73]
	v_mfma_f32_16x16x32_bf16 v[66:69], v[248:251], v[202:205], v[66:69]
	s_setprio 0
	v_readfirstlane_b32 s12, v149
	s_addk_i32 s50, 0x180
	s_mov_b32 m0, s12
	v_readfirstlane_b32 s12, v150
	s_barrier
	ds_read_b128 v[174:177], v135 offset:49152
	ds_read_b128 v[178:181], v135 offset:50176
	ds_read_b128 v[182:185], v134 offset:49152
	ds_read_b128 v[186:189], v134 offset:50176
	ds_read_b128 v[190:193], v133 offset:49152
	ds_read_b128 v[194:197], v133 offset:50176
	ds_read_b128 v[198:201], v132 offset:49152
	ds_read_b128 v[202:205], v132 offset:50176
	buffer_load_dwordx4 v136, s[4:7], s50 offen lds
	s_addk_i32 s29, 0x180
	s_mov_b32 m0, s12
	s_nop 0
	buffer_load_dwordx4 v136, s[4:7], s29 offen lds
	s_barrier
; #define WAIT_V(n) asm volatile("s_waitcnt vmcnt(" #n ")" ::: "memory")
; #define WAIT_L(n) asm volatile("s_waitcnt lgkmcnt(" #n ")" ::: "memory")
; #define BAR __builtin_amdgcn_s_barrier()
; #define SCHED __builtin_amdgcn_sched_barrier(0)
; template <int MODE>
; __device__ __forceinline__ void gemm_tile(const int ph, const int which, const int pm, const int pn) {
;     ...
;     BAR; WAIT_L(0); MMA(1, 0, At, B0); BAR; SCHED;
;     STAGE(SB(1, 1), RB, bcolB, t + 3);
;     WAIT_V(6); BAR; MMA(1, 1, At, B1); BAR;
;   }
;   {
;     LDB(B0, 0, 0); LDA(At, 0, 0); STAGE(SA(1, 1), RA, brow + HALF, nt - 1);
;     BAR; WAIT_L(0); MMA(0, 0, At, B0); BAR;
	s_waitcnt lgkmcnt(0)
	s_setprio 1
	s_waitcnt lgkmcnt(7)
	v_mfma_f32_16x16x32_bf16 v[62:65], v[158:161], v[174:177], v[62:65]
	v_mfma_f32_16x16x32_bf16 v[58:61], v[166:169], v[174:177], v[58:61]
	s_waitcnt lgkmcnt(5)
	v_mfma_f32_16x16x32_bf16 v[54:57], v[158:161], v[182:185], v[54:57]
	v_mfma_f32_16x16x32_bf16 v[50:53], v[166:169], v[182:185], v[50:53]
	s_waitcnt lgkmcnt(3)
	v_mfma_f32_16x16x32_bf16 v[46:49], v[158:161], v[190:193], v[46:49]
	v_mfma_f32_16x16x32_bf16 v[42:45], v[166:169], v[190:193], v[42:45]
	s_waitcnt lgkmcnt(1)
	v_mfma_f32_16x16x32_bf16 v[38:41], v[158:161], v[198:201], v[38:41]
	v_mfma_f32_16x16x32_bf16 v[34:37], v[166:169], v[198:201], v[34:37]
	v_mfma_f32_16x16x32_bf16 v[62:65], v[162:165], v[178:181], v[62:65]
	v_mfma_f32_16x16x32_bf16 v[58:61], v[170:173], v[178:181], v[58:61]
	v_mfma_f32_16x16x32_bf16 v[54:57], v[162:165], v[186:189], v[54:57]
	v_mfma_f32_16x16x32_bf16 v[50:53], v[170:173], v[186:189], v[50:53]
	v_mfma_f32_16x16x32_bf16 v[46:49], v[162:165], v[194:197], v[46:49]
	v_mfma_f32_16x16x32_bf16 v[42:45], v[170:173], v[194:197], v[42:45]
	s_waitcnt lgkmcnt(0)
	v_mfma_f32_16x16x32_bf16 v[38:41], v[162:165], v[202:205], v[38:41]
	v_mfma_f32_16x16x32_bf16 v[34:37], v[170:173], v[202:205], v[34:37]
	s_setprio 0
	s_barrier
	v_readfirstlane_b32 s12, v152
	s_addk_i32 s43, 0x180
	s_mov_b32 m0, s12
	v_readfirstlane_b32 s12, v154
	buffer_load_dwordx4 v136, s[68:71], s43 offen lds
	s_addk_i32 s38, 0x180
	s_mov_b32 m0, s12
	s_nop 0
	buffer_load_dwordx4 v136, s[68:71], s38 offen lds
	s_waitcnt vmcnt(6)
	s_barrier
	s_setprio 1
	v_mfma_f32_16x16x32_bf16 v[30:33], v[236:239], v[174:177], v[30:33]
	v_mfma_f32_16x16x32_bf16 v[26:29], v[244:247], v[174:177], v[26:29]
	v_mfma_f32_16x16x32_bf16 v[22:25], v[236:239], v[182:185], v[22:25]
	v_mfma_f32_16x16x32_bf16 v[18:21], v[244:247], v[182:185], v[18:21]
	v_mfma_f32_16x16x32_bf16 v[14:17], v[236:239], v[190:193], v[14:17]
	v_mfma_f32_16x16x32_bf16 v[10:13], v[244:247], v[190:193], v[10:13]
	v_mfma_f32_16x16x32_bf16 v[6:9], v[236:239], v[198:201], v[6:9]
	v_mfma_f32_16x16x32_bf16 v[2:5], v[244:247], v[198:201], v[2:5]
	v_mfma_f32_16x16x32_bf16 v[30:33], v[240:243], v[178:181], v[30:33]
	v_mfma_f32_16x16x32_bf16 v[26:29], v[248:251], v[178:181], v[26:29]
	v_mfma_f32_16x16x32_bf16 v[22:25], v[240:243], v[186:189], v[22:25]
	v_mfma_f32_16x16x32_bf16 v[18:21], v[248:251], v[186:189], v[18:21]
	v_mfma_f32_16x16x32_bf16 v[14:17], v[240:243], v[194:197], v[14:17]
	v_mfma_f32_16x16x32_bf16 v[10:13], v[248:251], v[194:197], v[10:13]
	v_mfma_f32_16x16x32_bf16 v[6:9], v[240:243], v[202:205], v[6:9]
	v_mfma_f32_16x16x32_bf16 v[2:5], v[248:251], v[202:205], v[2:5]
	s_setprio 0
	s_addk_i32 s23, 0x100
	s_cmp_lt_u32 s25, s2
	s_cbranch_scc1 .Lgemm_head_540
	s_barrier
	s_add_i32 s2, s24, s9
	s_lshl_b32 s2, s2, 1
	v_readfirstlane_b32 s3, v153
	s_addk_i32 s2, 0xff80
	s_mov_b32 s6, s70
	s_mov_b32 s7, s71
	s_mov_b32 m0, s3
	v_readfirstlane_b32 s3, v151
	ds_read_b128 v[140:143], v156
	ds_read_b128 v[146:149], v156 offset:1024
	ds_read_b128 v[158:161], v156 offset:2048
	ds_read_b128 v[162:165], v156 offset:3072
	ds_read_b128 v[166:169], v135
	ds_read_b128 v[170:173], v135 offset:1024
	ds_read_b128 v[174:177], v134
	ds_read_b128 v[178:181], v134 offset:1024
	ds_read_b128 v[182:185], v133
	ds_read_b128 v[186:189], v133 offset:1024
	ds_read_b128 v[190:193], v132
	ds_read_b128 v[194:197], v132 offset:1024
	buffer_load_dwordx4 v136, s[4:7], s2 offen lds
	s_add_i32 s2, s2, s8
	s_mov_b32 m0, s3
	s_nop 0
	buffer_load_dwordx4 v136, s[4:7], s2 offen lds
	s_barrier
	s_waitcnt lgkmcnt(0)
	s_setprio 1
	s_waitcnt lgkmcnt(7)
	v_mfma_f32_16x16x32_bf16 v[126:129], v[140:143], v[166:169], v[126:129]
	v_mfma_f32_16x16x32_bf16 v[122:125], v[158:161], v[166:169], v[122:125]
	s_waitcnt lgkmcnt(3)
	v_mfma_f32_16x16x32_bf16 v[110:113], v[140:143], v[182:185], v[110:113]
	v_mfma_f32_16x16x32_bf16 v[106:109], v[158:161], v[182:185], v[106:109]
	v_mfma_f32_16x16x32_bf16 v[126:129], v[146:149], v[170:173], v[126:129]
	v_mfma_f32_16x16x32_bf16 v[122:125], v[162:165], v[170:173], v[122:125]
	v_mfma_f32_16x16x32_bf16 v[118:121], v[140:143], v[174:177], v[118:121]
	v_mfma_f32_16x16x32_bf16 v[114:117], v[158:161], v[174:177], v[114:117]
	s_waitcnt lgkmcnt(2)
	v_mfma_f32_16x16x32_bf16 v[110:113], v[146:149], v[186:189], v[110:113]
	v_mfma_f32_16x16x32_bf16 v[106:109], v[162:165], v[186:189], v[106:109]
	s_waitcnt lgkmcnt(1)
	v_mfma_f32_16x16x32_bf16 v[102:105], v[140:143], v[190:193], v[102:105]
	v_mfma_f32_16x16x32_bf16 v[98:101], v[158:161], v[190:193], v[98:101]
	v_mfma_f32_16x16x32_bf16 v[150:153], v[146:149], v[178:181], v[118:121]
	v_mfma_f32_16x16x32_bf16 v[198:201], v[162:165], v[178:181], v[114:117]
	s_waitcnt lgkmcnt(0)
	v_mfma_f32_16x16x32_bf16 v[202:205], v[146:149], v[194:197], v[102:105]
	v_mfma_f32_16x16x32_bf16 v[236:239], v[162:165], v[194:197], v[98:101]
	s_setprio 0
	s_barrier
	s_nop 0
	ds_read_b128 v[98:101], v155
	ds_read_b128 v[102:105], v155 offset:1024
	ds_read_b128 v[114:117], v155 offset:2048
	ds_read_b128 v[118:121], v155 offset:3072
	s_barrier
; #define WAIT_V(n) asm volatile("s_waitcnt vmcnt(" #n ")" ::: "memory")
; #define WAIT_L(n) asm volatile("s_waitcnt lgkmcnt(" #n ")" ::: "memory")
; #define BAR __builtin_amdgcn_s_barrier()
; template <int MODE>
; __device__ __forceinline__ void gemm_tile(const int ph, const int which, const int pm, const int pn) {
;     ...
;     LDB(B1, 0, 1); BAR; WAIT_L(0); MMA(0, 1, At, B1); BAR;
;     LDA(At, 0, 1); WAIT_V(4); BAR; WAIT_L(0); MMA(1, 0, At, B0); MMA(1, 1, At, B1); BAR;
;   }
;   {
;     LDB(B0, 1, 0); LDA(At, 1, 0); WAIT_V(2); BAR; WAIT_L(0); MMA(0, 0, At, B0); BAR;
	s_waitcnt lgkmcnt(0)
	s_setprio 1
	s_waitcnt lgkmcnt(3)
	v_mfma_f32_16x16x32_bf16 v[94:97], v[98:101], v[166:169], v[94:97]
	s_waitcnt lgkmcnt(1)
	v_mfma_f32_16x16x32_bf16 v[90:93], v[114:117], v[166:169], v[90:93]
	v_mfma_f32_16x16x32_bf16 v[78:81], v[98:101], v[182:185], v[78:81]
	v_mfma_f32_16x16x32_bf16 v[74:77], v[114:117], v[182:185], v[74:77]
	v_mfma_f32_16x16x32_bf16 v[70:73], v[98:101], v[190:193], v[70:73]
	v_mfma_f32_16x16x32_bf16 v[66:69], v[114:117], v[190:193], v[66:69]
	v_mfma_f32_16x16x32_bf16 v[94:97], v[102:105], v[170:173], v[94:97]
	s_waitcnt lgkmcnt(0)
	v_mfma_f32_16x16x32_bf16 v[90:93], v[118:121], v[170:173], v[90:93]
	v_mfma_f32_16x16x32_bf16 v[86:89], v[98:101], v[174:177], v[86:89]
	v_mfma_f32_16x16x32_bf16 v[82:85], v[114:117], v[174:177], v[82:85]
	v_mfma_f32_16x16x32_bf16 v[78:81], v[102:105], v[186:189], v[78:81]
	v_mfma_f32_16x16x32_bf16 v[74:77], v[118:121], v[186:189], v[74:77]
	v_mfma_f32_16x16x32_bf16 v[70:73], v[102:105], v[194:197], v[70:73]
	v_mfma_f32_16x16x32_bf16 v[66:69], v[118:121], v[194:197], v[66:69]
	v_mfma_f32_16x16x32_bf16 v[154:157], v[102:105], v[178:181], v[86:89]
	v_mfma_f32_16x16x32_bf16 v[166:169], v[118:121], v[178:181], v[82:85]
	s_setprio 0
	s_barrier
	s_nop 0
	ds_read_b128 v[82:85], v135 offset:16384
	ds_read_b128 v[86:89], v135 offset:17408
	ds_read_b128 v[170:173], v134 offset:16384
	ds_read_b128 v[174:177], v134 offset:17408
	ds_read_b128 v[178:181], v133 offset:16384
	ds_read_b128 v[182:185], v133 offset:17408
	ds_read_b128 v[186:189], v132 offset:16384
	ds_read_b128 v[190:193], v132 offset:17408
	s_waitcnt vmcnt(4)
	s_barrier
	s_waitcnt lgkmcnt(0)
	s_setprio 1
	s_waitcnt lgkmcnt(7)
	v_mfma_f32_16x16x32_bf16 v[62:65], v[140:143], v[82:85], v[62:65]
	s_waitcnt lgkmcnt(3)
	v_mfma_f32_16x16x32_bf16 v[46:49], v[140:143], v[178:181], v[46:49]
	v_mfma_f32_16x16x32_bf16 v[42:45], v[158:161], v[178:181], v[42:45]
	v_mfma_f32_16x16x32_bf16 v[62:65], v[146:149], v[86:89], v[62:65]
	v_mfma_f32_16x16x32_bf16 v[58:61], v[158:161], v[82:85], v[58:61]
	v_mfma_f32_16x16x32_bf16 v[54:57], v[140:143], v[170:173], v[54:57]
	v_mfma_f32_16x16x32_bf16 v[50:53], v[158:161], v[170:173], v[50:53]
	s_waitcnt lgkmcnt(2)
	v_mfma_f32_16x16x32_bf16 v[46:49], v[146:149], v[182:185], v[46:49]
	v_mfma_f32_16x16x32_bf16 v[42:45], v[162:165], v[182:185], v[42:45]
	s_waitcnt lgkmcnt(1)
	v_mfma_f32_16x16x32_bf16 v[38:41], v[140:143], v[186:189], v[38:41]
	v_mfma_f32_16x16x32_bf16 v[34:37], v[158:161], v[186:189], v[34:37]
	v_mfma_f32_16x16x32_bf16 v[194:197], v[162:165], v[86:89], v[58:61]
	v_mfma_f32_16x16x32_bf16 v[240:243], v[146:149], v[174:177], v[54:57]
	v_mfma_f32_16x16x32_bf16 v[244:247], v[162:165], v[174:177], v[50:53]
	s_waitcnt lgkmcnt(0)
	v_mfma_f32_16x16x32_bf16 v[140:143], v[146:149], v[190:193], v[38:41]
	v_mfma_f32_16x16x32_bf16 v[146:149], v[162:165], v[190:193], v[34:37]
	v_mfma_f32_16x16x32_bf16 v[30:33], v[98:101], v[82:85], v[30:33]
	v_mfma_f32_16x16x32_bf16 v[26:29], v[114:117], v[82:85], v[26:29]
	v_mfma_f32_16x16x32_bf16 v[14:17], v[98:101], v[178:181], v[14:17]
	v_mfma_f32_16x16x32_bf16 v[10:13], v[114:117], v[178:181], v[10:13]
	v_mfma_f32_16x16x32_bf16 v[30:33], v[102:105], v[86:89], v[30:33]
	v_mfma_f32_16x16x32_bf16 v[26:29], v[118:121], v[86:89], v[26:29]
	v_mfma_f32_16x16x32_bf16 v[22:25], v[98:101], v[170:173], v[22:25]
	v_mfma_f32_16x16x32_bf16 v[18:21], v[114:117], v[170:173], v[18:21]
	v_mfma_f32_16x16x32_bf16 v[14:17], v[102:105], v[182:185], v[14:17]
	v_mfma_f32_16x16x32_bf16 v[10:13], v[118:121], v[182:185], v[10:13]
	v_mfma_f32_16x16x32_bf16 v[6:9], v[98:101], v[186:189], v[6:9]
	v_mfma_f32_16x16x32_bf16 v[2:5], v[114:117], v[186:189], v[2:5]
	v_mfma_f32_16x16x32_bf16 v[158:161], v[102:105], v[174:177], v[22:25]
	v_mfma_f32_16x16x32_bf16 v[162:165], v[118:121], v[174:177], v[18:21]
	v_mfma_f32_16x16x32_bf16 v[170:173], v[102:105], v[190:193], v[6:9]
	v_mfma_f32_16x16x32_bf16 v[174:177], v[118:121], v[190:193], v[2:5]
	s_setprio 0
	s_barrier
	s_nop 1
	ds_read_b128 v[2:5], v144
	ds_read_b128 v[6:9], v144 offset:1024
	ds_read_b128 v[178:181], v144 offset:2048
	ds_read_b128 v[182:185], v144 offset:3072
	ds_read_b128 v[18:21], v135 offset:32768
	ds_read_b128 v[22:25], v135 offset:33792
	ds_read_b128 v[34:37], v134 offset:32768
	ds_read_b128 v[38:41], v134 offset:33792
	ds_read_b128 v[58:61], v133 offset:32768
	ds_read_b128 v[186:189], v133 offset:33792
	ds_read_b128 v[190:193], v132 offset:32768
	ds_read_b128 v[248:251], v132 offset:33792
	s_waitcnt vmcnt(2)
	s_barrier
; #define WAIT_V(n) asm volatile("s_waitcnt vmcnt(" #n ")" ::: "memory")
; #define WAIT_L(n) asm volatile("s_waitcnt lgkmcnt(" #n ")" ::: "memory")
; #define BAR __builtin_amdgcn_s_barrier()
; template <int MODE>
; __device__ __forceinline__ void gemm_tile(const int ph, const int which, const int pm, const int pn) {
;     ...
;     LDB(B0, 1, 0); LDA(At, 1, 0); WAIT_V(2); BAR; WAIT_L(0); MMA(0, 0, At, B0); BAR;
;     LDB(B1, 1, 1); WAIT_V(0); BAR; WAIT_L(0); MMA(0, 1, At, B1); BAR;
;     LDA(At, 1, 1); BAR; WAIT_L(0); MMA(1, 0, At, B0); MMA(1, 1, At, B1); BAR;
;   }
;   if (wr == 0) BAR;
	s_waitcnt lgkmcnt(0)
	s_setprio 1
	s_waitcnt lgkmcnt(7)
	v_mfma_f32_16x16x32_bf16 v[50:53], v[2:5], v[18:21], v[126:129]
	s_waitcnt lgkmcnt(6)
	v_mfma_f32_16x16x32_bf16 v[114:117], v[6:9], v[22:25], v[50:53]
	v_mfma_f32_16x16x32_bf16 v[50:53], v[178:181], v[18:21], v[122:125]
	v_mfma_f32_16x16x32_bf16 v[118:121], v[182:185], v[22:25], v[50:53]
	s_waitcnt lgkmcnt(5)
	v_mfma_f32_16x16x32_bf16 v[50:53], v[2:5], v[34:37], v[150:153]
	s_waitcnt lgkmcnt(4)
	v_mfma_f32_16x16x32_bf16 v[98:101], v[6:9], v[38:41], v[50:53]
	v_mfma_f32_16x16x32_bf16 v[50:53], v[178:181], v[34:37], v[198:201]
	v_mfma_f32_16x16x32_bf16 v[102:105], v[182:185], v[38:41], v[50:53]
	s_waitcnt lgkmcnt(3)
	v_mfma_f32_16x16x32_bf16 v[50:53], v[2:5], v[58:61], v[110:113]
	s_waitcnt lgkmcnt(2)
	v_mfma_f32_16x16x32_bf16 v[82:85], v[6:9], v[186:189], v[50:53]
	v_mfma_f32_16x16x32_bf16 v[50:53], v[178:181], v[58:61], v[106:109]
	v_mfma_f32_16x16x32_bf16 v[86:89], v[182:185], v[186:189], v[50:53]
	s_waitcnt lgkmcnt(1)
	v_mfma_f32_16x16x32_bf16 v[50:53], v[2:5], v[190:193], v[202:205]
	v_mfma_f32_16x16x32_bf16 v[54:57], v[178:181], v[190:193], v[236:239]
	s_waitcnt lgkmcnt(0)
	v_mfma_f32_16x16x32_bf16 v[50:53], v[6:9], v[248:251], v[50:53]
	v_mfma_f32_16x16x32_bf16 v[54:57], v[182:185], v[248:251], v[54:57]
	s_setprio 0
	s_barrier
	ds_read_b128 v[150:153], v138
	ds_read_b128 v[198:201], v138 offset:1024
	ds_read_b128 v[202:205], v138 offset:2048
	ds_read_b128 v[136:139], v138 offset:3072
	s_waitcnt vmcnt(0)
	s_barrier
	s_waitcnt lgkmcnt(0)
	s_setprio 1
	s_waitcnt lgkmcnt(3)
	v_mfma_f32_16x16x32_bf16 v[94:97], v[150:153], v[18:21], v[94:97]
	s_waitcnt lgkmcnt(1)
	v_mfma_f32_16x16x32_bf16 v[18:21], v[202:205], v[18:21], v[90:93]
	s_waitcnt lgkmcnt(0)
	v_mfma_f32_16x16x32_bf16 v[126:129], v[136:139], v[22:25], v[18:21]
	v_mfma_f32_16x16x32_bf16 v[18:21], v[150:153], v[34:37], v[154:157]
	v_mfma_f32_16x16x32_bf16 v[106:109], v[198:201], v[38:41], v[18:21]
	v_mfma_f32_16x16x32_bf16 v[18:21], v[202:205], v[34:37], v[166:169]
	v_mfma_f32_16x16x32_bf16 v[110:113], v[136:139], v[38:41], v[18:21]
	v_mfma_f32_16x16x32_bf16 v[18:21], v[150:153], v[58:61], v[78:81]
	v_mfma_f32_16x16x32_bf16 v[90:93], v[198:201], v[186:189], v[18:21]
	v_mfma_f32_16x16x32_bf16 v[18:21], v[202:205], v[58:61], v[74:77]
	v_mfma_f32_16x16x32_bf16 v[122:125], v[198:201], v[22:25], v[94:97]
	v_mfma_f32_16x16x32_bf16 v[94:97], v[136:139], v[186:189], v[18:21]
	v_mfma_f32_16x16x32_bf16 v[18:21], v[150:153], v[190:193], v[70:73]
	v_mfma_f32_16x16x32_bf16 v[74:77], v[198:201], v[248:251], v[18:21]
	v_mfma_f32_16x16x32_bf16 v[18:21], v[202:205], v[190:193], v[66:69]
	v_mfma_f32_16x16x32_bf16 v[78:81], v[136:139], v[248:251], v[18:21]
	s_setprio 0
	s_barrier
	ds_read_b128 v[70:73], v135 offset:49152
	ds_read_b128 v[154:157], v135 offset:50176
	ds_read_b128 v[166:169], v134 offset:49152
	ds_read_b128 v[186:189], v134 offset:50176
	ds_read_b128 v[190:193], v133 offset:49152
	ds_read_b128 v[236:239], v133 offset:50176
	ds_read_b128 v[248:251], v132 offset:49152
	ds_read_b128 v[132:135], v132 offset:50176
	s_barrier
	s_waitcnt lgkmcnt(0)
	s_setprio 1
	s_waitcnt lgkmcnt(7)
	v_mfma_f32_16x16x32_bf16 v[18:21], v[2:5], v[70:73], v[62:65]
	s_waitcnt lgkmcnt(6)
	v_mfma_f32_16x16x32_bf16 v[58:61], v[6:9], v[154:157], v[18:21]
	v_mfma_f32_16x16x32_bf16 v[18:21], v[178:181], v[70:73], v[194:197]
	v_mfma_f32_16x16x32_bf16 v[62:65], v[182:185], v[154:157], v[18:21]
	s_waitcnt lgkmcnt(5)
	v_mfma_f32_16x16x32_bf16 v[18:21], v[2:5], v[166:169], v[240:243]
	s_waitcnt lgkmcnt(4)
	v_mfma_f32_16x16x32_bf16 v[34:37], v[6:9], v[186:189], v[18:21]
	v_mfma_f32_16x16x32_bf16 v[18:21], v[178:181], v[166:169], v[244:247]
	v_mfma_f32_16x16x32_bf16 v[38:41], v[182:185], v[186:189], v[18:21]
	s_waitcnt lgkmcnt(3)
	v_mfma_f32_16x16x32_bf16 v[18:21], v[2:5], v[190:193], v[46:49]
	s_waitcnt lgkmcnt(1)
	v_mfma_f32_16x16x32_bf16 v[2:5], v[2:5], v[248:251], v[140:143]
	v_mfma_f32_16x16x32_bf16 v[18:21], v[6:9], v[236:239], v[18:21]
	v_mfma_f32_16x16x32_bf16 v[22:25], v[178:181], v[190:193], v[42:45]
	s_waitcnt lgkmcnt(0)
	v_mfma_f32_16x16x32_bf16 v[2:5], v[6:9], v[132:135], v[2:5]
	v_mfma_f32_16x16x32_bf16 v[6:9], v[178:181], v[248:251], v[146:149]
	v_mfma_f32_16x16x32_bf16 v[22:25], v[182:185], v[236:239], v[22:25]
	v_mfma_f32_16x16x32_bf16 v[6:9], v[182:185], v[132:135], v[6:9]
	v_mfma_f32_16x16x32_bf16 v[26:29], v[202:205], v[70:73], v[26:29]
	v_mfma_f32_16x16x32_bf16 v[30:33], v[150:153], v[70:73], v[30:33]
	v_mfma_f32_16x16x32_bf16 v[70:73], v[136:139], v[154:157], v[26:29]
	v_mfma_f32_16x16x32_bf16 v[26:29], v[150:153], v[166:169], v[158:161]
	v_mfma_f32_16x16x32_bf16 v[42:45], v[198:201], v[186:189], v[26:29]
	v_mfma_f32_16x16x32_bf16 v[26:29], v[202:205], v[166:169], v[162:165]
	v_mfma_f32_16x16x32_bf16 v[14:17], v[150:153], v[190:193], v[14:17]
	v_mfma_f32_16x16x32_bf16 v[10:13], v[202:205], v[190:193], v[10:13]
	v_mfma_f32_16x16x32_bf16 v[66:69], v[198:201], v[154:157], v[30:33]
	v_mfma_f32_16x16x32_bf16 v[46:49], v[136:139], v[186:189], v[26:29]
	v_mfma_f32_16x16x32_bf16 v[26:29], v[198:201], v[236:239], v[14:17]
	v_mfma_f32_16x16x32_bf16 v[30:33], v[136:139], v[236:239], v[10:13]
	v_mfma_f32_16x16x32_bf16 v[10:13], v[150:153], v[248:251], v[170:173]
	v_mfma_f32_16x16x32_bf16 v[14:17], v[202:205], v[248:251], v[174:177]
	v_mfma_f32_16x16x32_bf16 v[10:13], v[198:201], v[132:135], v[10:13]
	v_mfma_f32_16x16x32_bf16 v[14:17], v[136:139], v[132:135], v[14:17]
	s_setprio 0
	s_movk_i32 s2, 0x100
	v_cmp_gt_u32_e32 vcc, s2, v0
	s_barrier
	s_and_saveexec_b64 s[2:3], vcc
	s_cbranch_execz .LBB0_543
	s_barrier
